# ssd_local conv+silu loop hand-written, next iteration's 14 loads in flight (two register sets)
# speedup vs baseline: 1.0079x; 1.0079x over previous
.LBB0_214:
	s_mul_i32 s4, s12, 0x180
	s_sub_i32 s4, 0x200, s4
	v_mov_b32_e32 v42, s4
	v_mov_b32_e32 v49, v166
	v_mul_hi_i32 v43, v49, s67
	v_ashrrev_i32_e32 v43, 4, v43
	v_mul_lo_u32 v50, v43, s52
	v_sub_u32_e32 v44, v49, v50
	v_lshl_add_u32 v45, v44, 3, s71
	v_cmp_lt_u32_e32 vcc, 63, v44
	s_nop 1
	v_cndmask_b32_e64 v50, 0, 1, vcc
	v_mad_u32_u24 v45, v50, v42, v45
	v_cmp_lt_u32_e32 vcc, 79, v44
	s_nop 1
	v_cndmask_b32_e64 v50, 0, 1, vcc
	v_lshl_add_u32 v45, v50, 7, v45
	v_lshlrev_b32_e32 v50, 2, v45
	global_load_dwordx4 v[56:59], v50, s[78:79]
	global_load_dwordx4 v[60:63], v50, s[78:79] offset:16
	v_mul_u32_u24_e32 v51, 0x3600, v43
	v_lshl_add_u32 v51, v45, 1, v51
	s_add_u32 s4, s6, 0xffff8600
	s_addc_u32 s5, s7, -1
	global_load_dwordx4 v[64:67], v51, s[4:5]
	s_add_u32 s4, s6, 0xffffbc00
	s_addc_u32 s5, s7, -1
	global_load_dwordx4 v[68:71], v51, s[4:5]
	s_add_u32 s4, s6, 0xfffff200
	s_addc_u32 s5, s7, -1
	global_load_dwordx4 v[72:75], v51, s[4:5]
	s_add_u32 s4, s6, 0x2800
	s_addc_u32 s5, s7, 0
	global_load_dwordx4 v[76:79], v51, s[4:5]
	global_load_dwordx4 v[80:83], v50, s[92:93]
	global_load_dwordx4 v[84:87], v50, s[92:93] offset:16
	s_add_u32 s4, s92, 0x1800
	s_addc_u32 s5, s93, 0
	global_load_dwordx4 v[88:91], v50, s[4:5]
	global_load_dwordx4 v[92:95], v50, s[4:5] offset:16
	s_add_u32 s4, s92, 0x3000
	s_addc_u32 s5, s93, 0
	global_load_dwordx4 v[96:99], v50, s[4:5]
	global_load_dwordx4 v[100:103], v50, s[4:5] offset:16
	s_add_u32 s4, s92, 0x4800
	s_addc_u32 s5, s93, 0
	global_load_dwordx4 v[104:107], v50, s[4:5]
	global_load_dwordx4 v[108:111], v50, s[4:5] offset:16
	v_add_u32_e32 v49, 512, v166
	v_mul_hi_i32 v46, v49, s67
	v_ashrrev_i32_e32 v46, 4, v46
	v_mul_lo_u32 v50, v46, s52
	v_sub_u32_e32 v47, v49, v50
	v_lshl_add_u32 v48, v47, 3, s71
	v_cmp_lt_u32_e32 vcc, 63, v47
	s_nop 1
	v_cndmask_b32_e64 v50, 0, 1, vcc
	v_mad_u32_u24 v48, v50, v42, v48
	v_cmp_lt_u32_e32 vcc, 79, v47
	s_nop 1
	v_cndmask_b32_e64 v50, 0, 1, vcc
	v_lshl_add_u32 v48, v50, 7, v48
	v_lshlrev_b32_e32 v50, 2, v48
	global_load_dwordx4 v[112:115], v50, s[78:79]
	global_load_dwordx4 v[116:119], v50, s[78:79] offset:16
	v_mul_u32_u24_e32 v51, 0x3600, v46
	v_lshl_add_u32 v51, v48, 1, v51
	s_add_u32 s4, s6, 0xffff8600
	s_addc_u32 s5, s7, -1
	global_load_dwordx4 v[120:123], v51, s[4:5]
	s_add_u32 s4, s6, 0xffffbc00
	s_addc_u32 s5, s7, -1
	global_load_dwordx4 v[124:127], v51, s[4:5]
	s_add_u32 s4, s6, 0xfffff200
	s_addc_u32 s5, s7, -1
	global_load_dwordx4 v[128:131], v51, s[4:5]
	s_add_u32 s4, s6, 0x2800
	s_addc_u32 s5, s7, 0
	global_load_dwordx4 v[132:135], v51, s[4:5]
	global_load_dwordx4 v[136:139], v50, s[92:93]
	global_load_dwordx4 v[140:143], v50, s[92:93] offset:16
	s_add_u32 s4, s92, 0x1800
	s_addc_u32 s5, s93, 0
	global_load_dwordx4 v[144:147], v50, s[4:5]
	global_load_dwordx4 v[148:151], v50, s[4:5] offset:16
	s_add_u32 s4, s92, 0x3000
	s_addc_u32 s5, s93, 0
	global_load_dwordx4 v[152:155], v50, s[4:5]
	global_load_dwordx4 v[156:159], v50, s[4:5] offset:16
	s_add_u32 s4, s92, 0x4800
	s_addc_u32 s5, s93, 0
	global_load_dwordx4 v[160:163], v50, s[4:5]
	global_load_dwordx4 v[252:255], v50, s[4:5] offset:16
	s_waitcnt vmcnt(14)
	v_lshrrev_b32_e32 v49, 3, v44
	v_lshl_add_u32 v49, v49, 6, v43
	v_lshlrev_b32_e32 v49, 2, v49
	v_add_u32_e32 v49, 0x15000, v49
	ds_read_b32 v55, v49
	s_cmp_eq_u32 s68, 0
	s_cbranch_scc0 .Lsc_nomask_0
	v_cmp_gt_u32_e32 vcc, 3, v43
	s_nop 1
	v_cndmask_b32_e64 v64, v64, 0, vcc
	v_cndmask_b32_e64 v65, v65, 0, vcc
	v_cndmask_b32_e64 v66, v66, 0, vcc
	v_cndmask_b32_e64 v67, v67, 0, vcc
	v_cmp_gt_u32_e32 vcc, 2, v43
	s_nop 1
	v_cndmask_b32_e64 v68, v68, 0, vcc
	v_cndmask_b32_e64 v69, v69, 0, vcc
	v_cndmask_b32_e64 v70, v70, 0, vcc
	v_cndmask_b32_e64 v71, v71, 0, vcc
	v_cmp_gt_u32_e32 vcc, 1, v43
	s_nop 1
	v_cndmask_b32_e64 v72, v72, 0, vcc
	v_cndmask_b32_e64 v73, v73, 0, vcc
	v_cndmask_b32_e64 v74, v74, 0, vcc
	v_cndmask_b32_e64 v75, v75, 0, vcc
.Lsc_nomask_0:
	v_lshlrev_b32_e32 v49, 16, v64
	v_and_b32_e32 v64, 0xffff0000, v64
	v_fmac_f32_e32 v56, v80, v49
	v_fmac_f32_e32 v57, v81, v64
	v_lshlrev_b32_e32 v49, 16, v65
	v_and_b32_e32 v65, 0xffff0000, v65
	v_fmac_f32_e32 v58, v82, v49
	v_fmac_f32_e32 v59, v83, v65
	v_lshlrev_b32_e32 v49, 16, v66
	v_and_b32_e32 v66, 0xffff0000, v66
	v_fmac_f32_e32 v60, v84, v49
	v_fmac_f32_e32 v61, v85, v66
	v_lshlrev_b32_e32 v49, 16, v67
	v_and_b32_e32 v67, 0xffff0000, v67
	v_fmac_f32_e32 v62, v86, v49
	v_fmac_f32_e32 v63, v87, v67
	v_lshlrev_b32_e32 v49, 16, v68
	v_and_b32_e32 v68, 0xffff0000, v68
	v_fmac_f32_e32 v56, v88, v49
	v_fmac_f32_e32 v57, v89, v68
	v_lshlrev_b32_e32 v49, 16, v69
	v_and_b32_e32 v69, 0xffff0000, v69
	v_fmac_f32_e32 v58, v90, v49
	v_fmac_f32_e32 v59, v91, v69
	v_lshlrev_b32_e32 v49, 16, v70
	v_and_b32_e32 v70, 0xffff0000, v70
	v_fmac_f32_e32 v60, v92, v49
	v_fmac_f32_e32 v61, v93, v70
	v_lshlrev_b32_e32 v49, 16, v71
	v_and_b32_e32 v71, 0xffff0000, v71
	v_fmac_f32_e32 v62, v94, v49
	v_fmac_f32_e32 v63, v95, v71
	v_lshlrev_b32_e32 v49, 16, v72
	v_and_b32_e32 v72, 0xffff0000, v72
	v_fmac_f32_e32 v56, v96, v49
	v_fmac_f32_e32 v57, v97, v72
	v_lshlrev_b32_e32 v49, 16, v73
	v_and_b32_e32 v73, 0xffff0000, v73
	v_fmac_f32_e32 v58, v98, v49
	v_fmac_f32_e32 v59, v99, v73
	v_lshlrev_b32_e32 v49, 16, v74
	v_and_b32_e32 v74, 0xffff0000, v74
	v_fmac_f32_e32 v60, v100, v49
	v_fmac_f32_e32 v61, v101, v74
	v_lshlrev_b32_e32 v49, 16, v75
	v_and_b32_e32 v75, 0xffff0000, v75
	v_fmac_f32_e32 v62, v102, v49
	v_fmac_f32_e32 v63, v103, v75
	v_lshlrev_b32_e32 v49, 16, v76
	v_and_b32_e32 v76, 0xffff0000, v76
	v_fmac_f32_e32 v56, v104, v49
	v_fmac_f32_e32 v57, v105, v76
	v_lshlrev_b32_e32 v49, 16, v77
	v_and_b32_e32 v77, 0xffff0000, v77
	v_fmac_f32_e32 v58, v106, v49
	v_fmac_f32_e32 v59, v107, v77
	v_lshlrev_b32_e32 v49, 16, v78
	v_and_b32_e32 v78, 0xffff0000, v78
	v_fmac_f32_e32 v60, v108, v49
	v_fmac_f32_e32 v61, v109, v78
	v_lshlrev_b32_e32 v49, 16, v79
	v_and_b32_e32 v79, 0xffff0000, v79
	v_fmac_f32_e32 v62, v110, v49
	v_fmac_f32_e32 v63, v111, v79
	v_mul_f32_e32 v49, 0xbfb8aa3b, v56
	v_mul_f32_e32 v50, 0xbfb8aa3b, v57
	v_exp_f32_e32 v49, v49
	v_exp_f32_e32 v50, v50
	v_add_f32_e32 v49, 1.0, v49
	v_add_f32_e32 v50, 1.0, v50
	v_rcp_f32_e32 v49, v49
	v_rcp_f32_e32 v50, v50
	v_mul_f32_e32 v56, v56, v49
	v_mul_f32_e32 v57, v57, v50
	v_mul_f32_e32 v49, 0xbfb8aa3b, v58
	v_mul_f32_e32 v50, 0xbfb8aa3b, v59
	v_exp_f32_e32 v49, v49
	v_exp_f32_e32 v50, v50
	v_add_f32_e32 v49, 1.0, v49
	v_add_f32_e32 v50, 1.0, v50
	v_rcp_f32_e32 v49, v49
	v_rcp_f32_e32 v50, v50
	v_mul_f32_e32 v58, v58, v49
	v_mul_f32_e32 v59, v59, v50
	v_mul_f32_e32 v49, 0xbfb8aa3b, v60
	v_mul_f32_e32 v50, 0xbfb8aa3b, v61
	v_exp_f32_e32 v49, v49
	v_exp_f32_e32 v50, v50
	v_add_f32_e32 v49, 1.0, v49
	v_add_f32_e32 v50, 1.0, v50
	v_rcp_f32_e32 v49, v49
	v_rcp_f32_e32 v50, v50
	v_mul_f32_e32 v60, v60, v49
	v_mul_f32_e32 v61, v61, v50
	v_mul_f32_e32 v49, 0xbfb8aa3b, v62
	v_mul_f32_e32 v50, 0xbfb8aa3b, v63
	v_exp_f32_e32 v49, v49
	v_exp_f32_e32 v50, v50
	v_add_f32_e32 v49, 1.0, v49
	v_add_f32_e32 v50, 1.0, v50
	v_rcp_f32_e32 v49, v49
	v_rcp_f32_e32 v50, v50
	v_mul_f32_e32 v62, v62, v49
	v_mul_f32_e32 v63, v63, v50
	v_cvt_pk_bf16_f32 v64, v56, v57
	v_cvt_pk_bf16_f32 v65, v58, v59
	v_cvt_pk_bf16_f32 v66, v60, v61
	v_cvt_pk_bf16_f32 v67, v62, v63
	v_mul_u32_u24_e32 v49, 0xc00, v43
	v_lshl_add_u32 v49, v45, 1, v49
	global_store_dwordx4 v49, v[64:67], s[8:9]
	s_waitcnt lgkmcnt(0)
	v_mul_f32_e32 v244, v56, v55
	v_mul_f32_e32 v245, v57, v55
	v_mul_f32_e32 v246, v58, v55
	v_mul_f32_e32 v247, v59, v55
	v_mul_f32_e32 v248, v60, v55
	v_mul_f32_e32 v249, v61, v55
	v_mul_f32_e32 v250, v62, v55
	v_mul_f32_e32 v251, v63, v55
	v_cvt_pk_bf16_f32 v68, v244, v245
	v_cvt_pk_bf16_f32 v69, v246, v247
	v_cvt_pk_bf16_f32 v70, v248, v249
	v_cvt_pk_bf16_f32 v71, v250, v251
	v_mul_u32_u24_e32 v49, 0x420, v43
	v_lshl_add_u32 v49, v44, 4, v49
	v_mul_u32_u24_e32 v50, 0x120, v43
	v_lshl_add_u32 v50, v44, 4, v50
	v_add_u32_e32 v50, 0x10400, v50
	v_cmp_gt_u32_e32 vcc, 64, v44
	s_nop 1
	v_cndmask_b32_e32 v49, v50, v49, vcc
	v_cndmask_b32_e32 v68, v64, v68, vcc
	v_cndmask_b32_e32 v69, v65, v69, vcc
	v_cndmask_b32_e32 v70, v66, v70, vcc
	v_cndmask_b32_e32 v71, v67, v71, vcc
	v_cmp_gt_u32_e32 vcc, 80, v44
	s_and_saveexec_b64 s[12:13], vcc
	ds_write_b128 v49, v[68:71]
	s_or_b64 exec, exec, s[12:13]
	v_add_u32_e32 v49, 1024, v166
	v_mul_hi_i32 v43, v49, s67
	v_ashrrev_i32_e32 v43, 4, v43
	v_mul_lo_u32 v50, v43, s52
	v_sub_u32_e32 v44, v49, v50
	v_lshl_add_u32 v45, v44, 3, s71
	v_cmp_lt_u32_e32 vcc, 63, v44
	s_nop 1
	v_cndmask_b32_e64 v50, 0, 1, vcc
	v_mad_u32_u24 v45, v50, v42, v45
	v_cmp_lt_u32_e32 vcc, 79, v44
	s_nop 1
	v_cndmask_b32_e64 v50, 0, 1, vcc
	v_lshl_add_u32 v45, v50, 7, v45
	v_lshlrev_b32_e32 v50, 2, v45
	global_load_dwordx4 v[56:59], v50, s[78:79]
	global_load_dwordx4 v[60:63], v50, s[78:79] offset:16
	v_mul_u32_u24_e32 v51, 0x3600, v43
	v_lshl_add_u32 v51, v45, 1, v51
	s_add_u32 s4, s6, 0xffff8600
	s_addc_u32 s5, s7, -1
	global_load_dwordx4 v[64:67], v51, s[4:5]
	s_add_u32 s4, s6, 0xffffbc00
	s_addc_u32 s5, s7, -1
	global_load_dwordx4 v[68:71], v51, s[4:5]
	s_add_u32 s4, s6, 0xfffff200
	s_addc_u32 s5, s7, -1
	global_load_dwordx4 v[72:75], v51, s[4:5]
	s_add_u32 s4, s6, 0x2800
	s_addc_u32 s5, s7, 0
	global_load_dwordx4 v[76:79], v51, s[4:5]
	global_load_dwordx4 v[80:83], v50, s[92:93]
	global_load_dwordx4 v[84:87], v50, s[92:93] offset:16
	s_add_u32 s4, s92, 0x1800
	s_addc_u32 s5, s93, 0
	global_load_dwordx4 v[88:91], v50, s[4:5]
	global_load_dwordx4 v[92:95], v50, s[4:5] offset:16
	s_add_u32 s4, s92, 0x3000
	s_addc_u32 s5, s93, 0
	global_load_dwordx4 v[96:99], v50, s[4:5]
	global_load_dwordx4 v[100:103], v50, s[4:5] offset:16
	s_add_u32 s4, s92, 0x4800
	s_addc_u32 s5, s93, 0
	global_load_dwordx4 v[104:107], v50, s[4:5]
	global_load_dwordx4 v[108:111], v50, s[4:5] offset:16
	s_waitcnt vmcnt(15)
	v_lshrrev_b32_e32 v49, 3, v47
	v_lshl_add_u32 v49, v49, 6, v46
	v_lshlrev_b32_e32 v49, 2, v49
	v_add_u32_e32 v49, 0x15000, v49
	ds_read_b32 v55, v49
	s_cmp_eq_u32 s68, 0
	s_cbranch_scc0 .Lsc_nomask_1
	v_cmp_gt_u32_e32 vcc, 3, v46
	s_nop 1
	v_cndmask_b32_e64 v120, v120, 0, vcc
	v_cndmask_b32_e64 v121, v121, 0, vcc
	v_cndmask_b32_e64 v122, v122, 0, vcc
	v_cndmask_b32_e64 v123, v123, 0, vcc
	v_cmp_gt_u32_e32 vcc, 2, v46
	s_nop 1
	v_cndmask_b32_e64 v124, v124, 0, vcc
	v_cndmask_b32_e64 v125, v125, 0, vcc
	v_cndmask_b32_e64 v126, v126, 0, vcc
	v_cndmask_b32_e64 v127, v127, 0, vcc
	v_cmp_gt_u32_e32 vcc, 1, v46
	s_nop 1
	v_cndmask_b32_e64 v128, v128, 0, vcc
	v_cndmask_b32_e64 v129, v129, 0, vcc
	v_cndmask_b32_e64 v130, v130, 0, vcc
	v_cndmask_b32_e64 v131, v131, 0, vcc
.Lsc_nomask_1:
	v_lshlrev_b32_e32 v49, 16, v120
	v_and_b32_e32 v120, 0xffff0000, v120
	v_fmac_f32_e32 v112, v136, v49
	v_fmac_f32_e32 v113, v137, v120
	v_lshlrev_b32_e32 v49, 16, v121
	v_and_b32_e32 v121, 0xffff0000, v121
	v_fmac_f32_e32 v114, v138, v49
	v_fmac_f32_e32 v115, v139, v121
	v_lshlrev_b32_e32 v49, 16, v122
	v_and_b32_e32 v122, 0xffff0000, v122
	v_fmac_f32_e32 v116, v140, v49
	v_fmac_f32_e32 v117, v141, v122
	v_lshlrev_b32_e32 v49, 16, v123
	v_and_b32_e32 v123, 0xffff0000, v123
	v_fmac_f32_e32 v118, v142, v49
	v_fmac_f32_e32 v119, v143, v123
	v_lshlrev_b32_e32 v49, 16, v124
	v_and_b32_e32 v124, 0xffff0000, v124
	v_fmac_f32_e32 v112, v144, v49
	v_fmac_f32_e32 v113, v145, v124
	v_lshlrev_b32_e32 v49, 16, v125
	v_and_b32_e32 v125, 0xffff0000, v125
	v_fmac_f32_e32 v114, v146, v49
	v_fmac_f32_e32 v115, v147, v125
	v_lshlrev_b32_e32 v49, 16, v126
	v_and_b32_e32 v126, 0xffff0000, v126
	v_fmac_f32_e32 v116, v148, v49
	v_fmac_f32_e32 v117, v149, v126
	v_lshlrev_b32_e32 v49, 16, v127
	v_and_b32_e32 v127, 0xffff0000, v127
	v_fmac_f32_e32 v118, v150, v49
	v_fmac_f32_e32 v119, v151, v127
	v_lshlrev_b32_e32 v49, 16, v128
	v_and_b32_e32 v128, 0xffff0000, v128
	v_fmac_f32_e32 v112, v152, v49
	v_fmac_f32_e32 v113, v153, v128
	v_lshlrev_b32_e32 v49, 16, v129
	v_and_b32_e32 v129, 0xffff0000, v129
	v_fmac_f32_e32 v114, v154, v49
	v_fmac_f32_e32 v115, v155, v129
	v_lshlrev_b32_e32 v49, 16, v130
	v_and_b32_e32 v130, 0xffff0000, v130
	v_fmac_f32_e32 v116, v156, v49
	v_fmac_f32_e32 v117, v157, v130
	v_lshlrev_b32_e32 v49, 16, v131
	v_and_b32_e32 v131, 0xffff0000, v131
	v_fmac_f32_e32 v118, v158, v49
	v_fmac_f32_e32 v119, v159, v131
	v_lshlrev_b32_e32 v49, 16, v132
	v_and_b32_e32 v132, 0xffff0000, v132
	v_fmac_f32_e32 v112, v160, v49
	v_fmac_f32_e32 v113, v161, v132
	v_lshlrev_b32_e32 v49, 16, v133
	v_and_b32_e32 v133, 0xffff0000, v133
	v_fmac_f32_e32 v114, v162, v49
	v_fmac_f32_e32 v115, v163, v133
	v_lshlrev_b32_e32 v49, 16, v134
	v_and_b32_e32 v134, 0xffff0000, v134
	v_fmac_f32_e32 v116, v252, v49
	v_fmac_f32_e32 v117, v253, v134
	v_lshlrev_b32_e32 v49, 16, v135
	v_and_b32_e32 v135, 0xffff0000, v135
	v_fmac_f32_e32 v118, v254, v49
	v_fmac_f32_e32 v119, v255, v135
	v_mul_f32_e32 v49, 0xbfb8aa3b, v112
	v_mul_f32_e32 v50, 0xbfb8aa3b, v113
	v_exp_f32_e32 v49, v49
	v_exp_f32_e32 v50, v50
	v_add_f32_e32 v49, 1.0, v49
	v_add_f32_e32 v50, 1.0, v50
	v_rcp_f32_e32 v49, v49
	v_rcp_f32_e32 v50, v50
	v_mul_f32_e32 v112, v112, v49
	v_mul_f32_e32 v113, v113, v50
	v_mul_f32_e32 v49, 0xbfb8aa3b, v114
	v_mul_f32_e32 v50, 0xbfb8aa3b, v115
	v_exp_f32_e32 v49, v49
	v_exp_f32_e32 v50, v50
	v_add_f32_e32 v49, 1.0, v49
	v_add_f32_e32 v50, 1.0, v50
	v_rcp_f32_e32 v49, v49
	v_rcp_f32_e32 v50, v50
	v_mul_f32_e32 v114, v114, v49
	v_mul_f32_e32 v115, v115, v50
	v_mul_f32_e32 v49, 0xbfb8aa3b, v116
	v_mul_f32_e32 v50, 0xbfb8aa3b, v117
	v_exp_f32_e32 v49, v49
	v_exp_f32_e32 v50, v50
	v_add_f32_e32 v49, 1.0, v49
	v_add_f32_e32 v50, 1.0, v50
	v_rcp_f32_e32 v49, v49
	v_rcp_f32_e32 v50, v50
	v_mul_f32_e32 v116, v116, v49
	v_mul_f32_e32 v117, v117, v50
	v_mul_f32_e32 v49, 0xbfb8aa3b, v118
	v_mul_f32_e32 v50, 0xbfb8aa3b, v119
	v_exp_f32_e32 v49, v49
	v_exp_f32_e32 v50, v50
	v_add_f32_e32 v49, 1.0, v49
	v_add_f32_e32 v50, 1.0, v50
	v_rcp_f32_e32 v49, v49
	v_rcp_f32_e32 v50, v50
	v_mul_f32_e32 v118, v118, v49
	v_mul_f32_e32 v119, v119, v50
	v_cvt_pk_bf16_f32 v120, v112, v113
	v_cvt_pk_bf16_f32 v121, v114, v115
	v_cvt_pk_bf16_f32 v122, v116, v117
	v_cvt_pk_bf16_f32 v123, v118, v119
	v_mul_u32_u24_e32 v49, 0xc00, v46
	v_lshl_add_u32 v49, v48, 1, v49
	global_store_dwordx4 v49, v[120:123], s[8:9]
	s_waitcnt lgkmcnt(0)
	v_mul_f32_e32 v244, v112, v55
	v_mul_f32_e32 v245, v113, v55
	v_mul_f32_e32 v246, v114, v55
	v_mul_f32_e32 v247, v115, v55
	v_mul_f32_e32 v248, v116, v55
	v_mul_f32_e32 v249, v117, v55
	v_mul_f32_e32 v250, v118, v55
	v_mul_f32_e32 v251, v119, v55
	v_cvt_pk_bf16_f32 v124, v244, v245
	v_cvt_pk_bf16_f32 v125, v246, v247
	v_cvt_pk_bf16_f32 v126, v248, v249
	v_cvt_pk_bf16_f32 v127, v250, v251
	v_mul_u32_u24_e32 v49, 0x420, v46
	v_lshl_add_u32 v49, v47, 4, v49
	v_mul_u32_u24_e32 v50, 0x120, v46
	v_lshl_add_u32 v50, v47, 4, v50
	v_add_u32_e32 v50, 0x10400, v50
	v_cmp_gt_u32_e32 vcc, 64, v47
	s_nop 1
	v_cndmask_b32_e32 v49, v50, v49, vcc
	v_cndmask_b32_e32 v124, v120, v124, vcc
	v_cndmask_b32_e32 v125, v121, v125, vcc
	v_cndmask_b32_e32 v126, v122, v126, vcc
	v_cndmask_b32_e32 v127, v123, v127, vcc
	v_cmp_gt_u32_e32 vcc, 80, v47
	s_and_saveexec_b64 s[12:13], vcc
	ds_write_b128 v49, v[124:127]
	s_or_b64 exec, exec, s[12:13]
	v_add_u32_e32 v49, 1536, v166
	v_mul_hi_i32 v46, v49, s67
	v_ashrrev_i32_e32 v46, 4, v46
	v_mul_lo_u32 v50, v46, s52
	v_sub_u32_e32 v47, v49, v50
	v_lshl_add_u32 v48, v47, 3, s71
	v_cmp_lt_u32_e32 vcc, 63, v47
	s_nop 1
	v_cndmask_b32_e64 v50, 0, 1, vcc
	v_mad_u32_u24 v48, v50, v42, v48
	v_cmp_lt_u32_e32 vcc, 79, v47
	s_nop 1
	v_cndmask_b32_e64 v50, 0, 1, vcc
	v_lshl_add_u32 v48, v50, 7, v48
	v_lshlrev_b32_e32 v50, 2, v48
	global_load_dwordx4 v[112:115], v50, s[78:79]
	global_load_dwordx4 v[116:119], v50, s[78:79] offset:16
	v_mul_u32_u24_e32 v51, 0x3600, v46
	v_lshl_add_u32 v51, v48, 1, v51
	s_add_u32 s4, s6, 0xffff8600
	s_addc_u32 s5, s7, -1
	global_load_dwordx4 v[120:123], v51, s[4:5]
	s_add_u32 s4, s6, 0xffffbc00
	s_addc_u32 s5, s7, -1
	global_load_dwordx4 v[124:127], v51, s[4:5]
	s_add_u32 s4, s6, 0xfffff200
	s_addc_u32 s5, s7, -1
	global_load_dwordx4 v[128:131], v51, s[4:5]
	s_add_u32 s4, s6, 0x2800
	s_addc_u32 s5, s7, 0
	global_load_dwordx4 v[132:135], v51, s[4:5]
	global_load_dwordx4 v[136:139], v50, s[92:93]
	global_load_dwordx4 v[140:143], v50, s[92:93] offset:16
	s_add_u32 s4, s92, 0x1800
	s_addc_u32 s5, s93, 0
	global_load_dwordx4 v[144:147], v50, s[4:5]
	global_load_dwordx4 v[148:151], v50, s[4:5] offset:16
	s_add_u32 s4, s92, 0x3000
	s_addc_u32 s5, s93, 0
	global_load_dwordx4 v[152:155], v50, s[4:5]
	global_load_dwordx4 v[156:159], v50, s[4:5] offset:16
	s_add_u32 s4, s92, 0x4800
	s_addc_u32 s5, s93, 0
	global_load_dwordx4 v[160:163], v50, s[4:5]
	global_load_dwordx4 v[252:255], v50, s[4:5] offset:16
	s_waitcnt vmcnt(15)
	v_lshrrev_b32_e32 v49, 3, v44
	v_lshl_add_u32 v49, v49, 6, v43
	v_lshlrev_b32_e32 v49, 2, v49
	v_add_u32_e32 v49, 0x15000, v49
	ds_read_b32 v55, v49
	s_cmp_eq_u32 s68, 0
	s_cbranch_scc0 .Lsc_nomask_2
	v_cmp_gt_u32_e32 vcc, 3, v43
	s_nop 1
	v_cndmask_b32_e64 v64, v64, 0, vcc
	v_cndmask_b32_e64 v65, v65, 0, vcc
	v_cndmask_b32_e64 v66, v66, 0, vcc
	v_cndmask_b32_e64 v67, v67, 0, vcc
	v_cmp_gt_u32_e32 vcc, 2, v43
	s_nop 1
	v_cndmask_b32_e64 v68, v68, 0, vcc
	v_cndmask_b32_e64 v69, v69, 0, vcc
	v_cndmask_b32_e64 v70, v70, 0, vcc
	v_cndmask_b32_e64 v71, v71, 0, vcc
	v_cmp_gt_u32_e32 vcc, 1, v43
	s_nop 1
	v_cndmask_b32_e64 v72, v72, 0, vcc
	v_cndmask_b32_e64 v73, v73, 0, vcc
	v_cndmask_b32_e64 v74, v74, 0, vcc
	v_cndmask_b32_e64 v75, v75, 0, vcc
.Lsc_nomask_2:
	v_lshlrev_b32_e32 v49, 16, v64
	v_and_b32_e32 v64, 0xffff0000, v64
	v_fmac_f32_e32 v56, v80, v49
	v_fmac_f32_e32 v57, v81, v64
	v_lshlrev_b32_e32 v49, 16, v65
	v_and_b32_e32 v65, 0xffff0000, v65
	v_fmac_f32_e32 v58, v82, v49
	v_fmac_f32_e32 v59, v83, v65
	v_lshlrev_b32_e32 v49, 16, v66
	v_and_b32_e32 v66, 0xffff0000, v66
	v_fmac_f32_e32 v60, v84, v49
	v_fmac_f32_e32 v61, v85, v66
	v_lshlrev_b32_e32 v49, 16, v67
	v_and_b32_e32 v67, 0xffff0000, v67
	v_fmac_f32_e32 v62, v86, v49
	v_fmac_f32_e32 v63, v87, v67
	v_lshlrev_b32_e32 v49, 16, v68
	v_and_b32_e32 v68, 0xffff0000, v68
	v_fmac_f32_e32 v56, v88, v49
	v_fmac_f32_e32 v57, v89, v68
	v_lshlrev_b32_e32 v49, 16, v69
	v_and_b32_e32 v69, 0xffff0000, v69
	v_fmac_f32_e32 v58, v90, v49
	v_fmac_f32_e32 v59, v91, v69
	v_lshlrev_b32_e32 v49, 16, v70
	v_and_b32_e32 v70, 0xffff0000, v70
	v_fmac_f32_e32 v60, v92, v49
	v_fmac_f32_e32 v61, v93, v70
	v_lshlrev_b32_e32 v49, 16, v71
	v_and_b32_e32 v71, 0xffff0000, v71
	v_fmac_f32_e32 v62, v94, v49
	v_fmac_f32_e32 v63, v95, v71
	v_lshlrev_b32_e32 v49, 16, v72
	v_and_b32_e32 v72, 0xffff0000, v72
	v_fmac_f32_e32 v56, v96, v49
	v_fmac_f32_e32 v57, v97, v72
	v_lshlrev_b32_e32 v49, 16, v73
	v_and_b32_e32 v73, 0xffff0000, v73
	v_fmac_f32_e32 v58, v98, v49
	v_fmac_f32_e32 v59, v99, v73
	v_lshlrev_b32_e32 v49, 16, v74
	v_and_b32_e32 v74, 0xffff0000, v74
	v_fmac_f32_e32 v60, v100, v49
	v_fmac_f32_e32 v61, v101, v74
	v_lshlrev_b32_e32 v49, 16, v75
	v_and_b32_e32 v75, 0xffff0000, v75
	v_fmac_f32_e32 v62, v102, v49
	v_fmac_f32_e32 v63, v103, v75
	v_lshlrev_b32_e32 v49, 16, v76
	v_and_b32_e32 v76, 0xffff0000, v76
	v_fmac_f32_e32 v56, v104, v49
	v_fmac_f32_e32 v57, v105, v76
	v_lshlrev_b32_e32 v49, 16, v77
	v_and_b32_e32 v77, 0xffff0000, v77
	v_fmac_f32_e32 v58, v106, v49
	v_fmac_f32_e32 v59, v107, v77
	v_lshlrev_b32_e32 v49, 16, v78
	v_and_b32_e32 v78, 0xffff0000, v78
	v_fmac_f32_e32 v60, v108, v49
	v_fmac_f32_e32 v61, v109, v78
	v_lshlrev_b32_e32 v49, 16, v79
	v_and_b32_e32 v79, 0xffff0000, v79
	v_fmac_f32_e32 v62, v110, v49
	v_fmac_f32_e32 v63, v111, v79
	v_mul_f32_e32 v49, 0xbfb8aa3b, v56
	v_mul_f32_e32 v50, 0xbfb8aa3b, v57
	v_exp_f32_e32 v49, v49
	v_exp_f32_e32 v50, v50
	v_add_f32_e32 v49, 1.0, v49
	v_add_f32_e32 v50, 1.0, v50
	v_rcp_f32_e32 v49, v49
	v_rcp_f32_e32 v50, v50
	v_mul_f32_e32 v56, v56, v49
	v_mul_f32_e32 v57, v57, v50
	v_mul_f32_e32 v49, 0xbfb8aa3b, v58
	v_mul_f32_e32 v50, 0xbfb8aa3b, v59
	v_exp_f32_e32 v49, v49
	v_exp_f32_e32 v50, v50
	v_add_f32_e32 v49, 1.0, v49
	v_add_f32_e32 v50, 1.0, v50
	v_rcp_f32_e32 v49, v49
	v_rcp_f32_e32 v50, v50
	v_mul_f32_e32 v58, v58, v49
	v_mul_f32_e32 v59, v59, v50
	v_mul_f32_e32 v49, 0xbfb8aa3b, v60
	v_mul_f32_e32 v50, 0xbfb8aa3b, v61
	v_exp_f32_e32 v49, v49
	v_exp_f32_e32 v50, v50
	v_add_f32_e32 v49, 1.0, v49
	v_add_f32_e32 v50, 1.0, v50
	v_rcp_f32_e32 v49, v49
	v_rcp_f32_e32 v50, v50
	v_mul_f32_e32 v60, v60, v49
	v_mul_f32_e32 v61, v61, v50
	v_mul_f32_e32 v49, 0xbfb8aa3b, v62
	v_mul_f32_e32 v50, 0xbfb8aa3b, v63
	v_exp_f32_e32 v49, v49
	v_exp_f32_e32 v50, v50
	v_add_f32_e32 v49, 1.0, v49
	v_add_f32_e32 v50, 1.0, v50
	v_rcp_f32_e32 v49, v49
	v_rcp_f32_e32 v50, v50
	v_mul_f32_e32 v62, v62, v49
	v_mul_f32_e32 v63, v63, v50
	v_cvt_pk_bf16_f32 v64, v56, v57
	v_cvt_pk_bf16_f32 v65, v58, v59
	v_cvt_pk_bf16_f32 v66, v60, v61
	v_cvt_pk_bf16_f32 v67, v62, v63
	v_mul_u32_u24_e32 v49, 0xc00, v43
	v_lshl_add_u32 v49, v45, 1, v49
	global_store_dwordx4 v49, v[64:67], s[8:9]
	s_waitcnt lgkmcnt(0)
	v_mul_f32_e32 v244, v56, v55
	v_mul_f32_e32 v245, v57, v55
	v_mul_f32_e32 v246, v58, v55
	v_mul_f32_e32 v247, v59, v55
	v_mul_f32_e32 v248, v60, v55
	v_mul_f32_e32 v249, v61, v55
	v_mul_f32_e32 v250, v62, v55
	v_mul_f32_e32 v251, v63, v55
	v_cvt_pk_bf16_f32 v68, v244, v245
	v_cvt_pk_bf16_f32 v69, v246, v247
	v_cvt_pk_bf16_f32 v70, v248, v249
	v_cvt_pk_bf16_f32 v71, v250, v251
	v_mul_u32_u24_e32 v49, 0x420, v43
	v_lshl_add_u32 v49, v44, 4, v49
	v_mul_u32_u24_e32 v50, 0x120, v43
	v_lshl_add_u32 v50, v44, 4, v50
	v_add_u32_e32 v50, 0x10400, v50
	v_cmp_gt_u32_e32 vcc, 64, v44
	s_nop 1
	v_cndmask_b32_e32 v49, v50, v49, vcc
	v_cndmask_b32_e32 v68, v64, v68, vcc
	v_cndmask_b32_e32 v69, v65, v69, vcc
	v_cndmask_b32_e32 v70, v66, v70, vcc
	v_cndmask_b32_e32 v71, v67, v71, vcc
	v_cmp_gt_u32_e32 vcc, 80, v44
	s_and_saveexec_b64 s[12:13], vcc
	ds_write_b128 v49, v[68:71]
	s_or_b64 exec, exec, s[12:13]
	v_add_u32_e32 v49, 2048, v166
	v_mul_hi_i32 v43, v49, s67
	v_ashrrev_i32_e32 v43, 4, v43
	v_mul_lo_u32 v50, v43, s52
	v_sub_u32_e32 v44, v49, v50
	v_lshl_add_u32 v45, v44, 3, s71
	v_cmp_lt_u32_e32 vcc, 63, v44
	s_nop 1
	v_cndmask_b32_e64 v50, 0, 1, vcc
	v_mad_u32_u24 v45, v50, v42, v45
	v_cmp_lt_u32_e32 vcc, 79, v44
	s_nop 1
	v_cndmask_b32_e64 v50, 0, 1, vcc
	v_lshl_add_u32 v45, v50, 7, v45
	v_lshlrev_b32_e32 v50, 2, v45
	global_load_dwordx4 v[56:59], v50, s[78:79]
	global_load_dwordx4 v[60:63], v50, s[78:79] offset:16
	v_mul_u32_u24_e32 v51, 0x3600, v43
	v_lshl_add_u32 v51, v45, 1, v51
	s_add_u32 s4, s6, 0xffff8600
	s_addc_u32 s5, s7, -1
	global_load_dwordx4 v[64:67], v51, s[4:5]
	s_add_u32 s4, s6, 0xffffbc00
	s_addc_u32 s5, s7, -1
	global_load_dwordx4 v[68:71], v51, s[4:5]
	s_add_u32 s4, s6, 0xfffff200
	s_addc_u32 s5, s7, -1
	global_load_dwordx4 v[72:75], v51, s[4:5]
	s_add_u32 s4, s6, 0x2800
	s_addc_u32 s5, s7, 0
	global_load_dwordx4 v[76:79], v51, s[4:5]
	global_load_dwordx4 v[80:83], v50, s[92:93]
	global_load_dwordx4 v[84:87], v50, s[92:93] offset:16
	s_add_u32 s4, s92, 0x1800
	s_addc_u32 s5, s93, 0
	global_load_dwordx4 v[88:91], v50, s[4:5]
	global_load_dwordx4 v[92:95], v50, s[4:5] offset:16
	s_add_u32 s4, s92, 0x3000
	s_addc_u32 s5, s93, 0
	global_load_dwordx4 v[96:99], v50, s[4:5]
	global_load_dwordx4 v[100:103], v50, s[4:5] offset:16
	s_add_u32 s4, s92, 0x4800
	s_addc_u32 s5, s93, 0
	global_load_dwordx4 v[104:107], v50, s[4:5]
	global_load_dwordx4 v[108:111], v50, s[4:5] offset:16
	s_waitcnt vmcnt(15)
	v_lshrrev_b32_e32 v49, 3, v47
	v_lshl_add_u32 v49, v49, 6, v46
	v_lshlrev_b32_e32 v49, 2, v49
	v_add_u32_e32 v49, 0x15000, v49
	ds_read_b32 v55, v49
	s_cmp_eq_u32 s68, 0
	s_cbranch_scc0 .Lsc_nomask_3
	v_cmp_gt_u32_e32 vcc, 3, v46
	s_nop 1
	v_cndmask_b32_e64 v120, v120, 0, vcc
	v_cndmask_b32_e64 v121, v121, 0, vcc
	v_cndmask_b32_e64 v122, v122, 0, vcc
	v_cndmask_b32_e64 v123, v123, 0, vcc
	v_cmp_gt_u32_e32 vcc, 2, v46
	s_nop 1
	v_cndmask_b32_e64 v124, v124, 0, vcc
	v_cndmask_b32_e64 v125, v125, 0, vcc
	v_cndmask_b32_e64 v126, v126, 0, vcc
	v_cndmask_b32_e64 v127, v127, 0, vcc
	v_cmp_gt_u32_e32 vcc, 1, v46
	s_nop 1
	v_cndmask_b32_e64 v128, v128, 0, vcc
	v_cndmask_b32_e64 v129, v129, 0, vcc
	v_cndmask_b32_e64 v130, v130, 0, vcc
	v_cndmask_b32_e64 v131, v131, 0, vcc
.Lsc_nomask_3:
	v_lshlrev_b32_e32 v49, 16, v120
	v_and_b32_e32 v120, 0xffff0000, v120
	v_fmac_f32_e32 v112, v136, v49
	v_fmac_f32_e32 v113, v137, v120
	v_lshlrev_b32_e32 v49, 16, v121
	v_and_b32_e32 v121, 0xffff0000, v121
	v_fmac_f32_e32 v114, v138, v49
	v_fmac_f32_e32 v115, v139, v121
	v_lshlrev_b32_e32 v49, 16, v122
	v_and_b32_e32 v122, 0xffff0000, v122
	v_fmac_f32_e32 v116, v140, v49
	v_fmac_f32_e32 v117, v141, v122
	v_lshlrev_b32_e32 v49, 16, v123
	v_and_b32_e32 v123, 0xffff0000, v123
	v_fmac_f32_e32 v118, v142, v49
	v_fmac_f32_e32 v119, v143, v123
	v_lshlrev_b32_e32 v49, 16, v124
	v_and_b32_e32 v124, 0xffff0000, v124
	v_fmac_f32_e32 v112, v144, v49
	v_fmac_f32_e32 v113, v145, v124
	v_lshlrev_b32_e32 v49, 16, v125
	v_and_b32_e32 v125, 0xffff0000, v125
	v_fmac_f32_e32 v114, v146, v49
	v_fmac_f32_e32 v115, v147, v125
	v_lshlrev_b32_e32 v49, 16, v126
	v_and_b32_e32 v126, 0xffff0000, v126
	v_fmac_f32_e32 v116, v148, v49
	v_fmac_f32_e32 v117, v149, v126
	v_lshlrev_b32_e32 v49, 16, v127
	v_and_b32_e32 v127, 0xffff0000, v127
	v_fmac_f32_e32 v118, v150, v49
	v_fmac_f32_e32 v119, v151, v127
	v_lshlrev_b32_e32 v49, 16, v128
	v_and_b32_e32 v128, 0xffff0000, v128
	v_fmac_f32_e32 v112, v152, v49
	v_fmac_f32_e32 v113, v153, v128
	v_lshlrev_b32_e32 v49, 16, v129
	v_and_b32_e32 v129, 0xffff0000, v129
	v_fmac_f32_e32 v114, v154, v49
	v_fmac_f32_e32 v115, v155, v129
	v_lshlrev_b32_e32 v49, 16, v130
	v_and_b32_e32 v130, 0xffff0000, v130
	v_fmac_f32_e32 v116, v156, v49
	v_fmac_f32_e32 v117, v157, v130
	v_lshlrev_b32_e32 v49, 16, v131
	v_and_b32_e32 v131, 0xffff0000, v131
	v_fmac_f32_e32 v118, v158, v49
	v_fmac_f32_e32 v119, v159, v131
	v_lshlrev_b32_e32 v49, 16, v132
	v_and_b32_e32 v132, 0xffff0000, v132
	v_fmac_f32_e32 v112, v160, v49
	v_fmac_f32_e32 v113, v161, v132
	v_lshlrev_b32_e32 v49, 16, v133
	v_and_b32_e32 v133, 0xffff0000, v133
	v_fmac_f32_e32 v114, v162, v49
	v_fmac_f32_e32 v115, v163, v133
	v_lshlrev_b32_e32 v49, 16, v134
	v_and_b32_e32 v134, 0xffff0000, v134
	v_fmac_f32_e32 v116, v252, v49
	v_fmac_f32_e32 v117, v253, v134
	v_lshlrev_b32_e32 v49, 16, v135
	v_and_b32_e32 v135, 0xffff0000, v135
	v_fmac_f32_e32 v118, v254, v49
	v_fmac_f32_e32 v119, v255, v135
	v_mul_f32_e32 v49, 0xbfb8aa3b, v112
	v_mul_f32_e32 v50, 0xbfb8aa3b, v113
	v_exp_f32_e32 v49, v49
	v_exp_f32_e32 v50, v50
	v_add_f32_e32 v49, 1.0, v49
	v_add_f32_e32 v50, 1.0, v50
	v_rcp_f32_e32 v49, v49
	v_rcp_f32_e32 v50, v50
	v_mul_f32_e32 v112, v112, v49
	v_mul_f32_e32 v113, v113, v50
	v_mul_f32_e32 v49, 0xbfb8aa3b, v114
	v_mul_f32_e32 v50, 0xbfb8aa3b, v115
	v_exp_f32_e32 v49, v49
	v_exp_f32_e32 v50, v50
	v_add_f32_e32 v49, 1.0, v49
	v_add_f32_e32 v50, 1.0, v50
	v_rcp_f32_e32 v49, v49
	v_rcp_f32_e32 v50, v50
	v_mul_f32_e32 v114, v114, v49
	v_mul_f32_e32 v115, v115, v50
	v_mul_f32_e32 v49, 0xbfb8aa3b, v116
	v_mul_f32_e32 v50, 0xbfb8aa3b, v117
	v_exp_f32_e32 v49, v49
	v_exp_f32_e32 v50, v50
	v_add_f32_e32 v49, 1.0, v49
	v_add_f32_e32 v50, 1.0, v50
	v_rcp_f32_e32 v49, v49
	v_rcp_f32_e32 v50, v50
	v_mul_f32_e32 v116, v116, v49
	v_mul_f32_e32 v117, v117, v50
	v_mul_f32_e32 v49, 0xbfb8aa3b, v118
	v_mul_f32_e32 v50, 0xbfb8aa3b, v119
	v_exp_f32_e32 v49, v49
	v_exp_f32_e32 v50, v50
	v_add_f32_e32 v49, 1.0, v49
	v_add_f32_e32 v50, 1.0, v50
	v_rcp_f32_e32 v49, v49
	v_rcp_f32_e32 v50, v50
	v_mul_f32_e32 v118, v118, v49
	v_mul_f32_e32 v119, v119, v50
	v_cvt_pk_bf16_f32 v120, v112, v113
	v_cvt_pk_bf16_f32 v121, v114, v115
	v_cvt_pk_bf16_f32 v122, v116, v117
	v_cvt_pk_bf16_f32 v123, v118, v119
	v_mul_u32_u24_e32 v49, 0xc00, v46
	v_lshl_add_u32 v49, v48, 1, v49
	global_store_dwordx4 v49, v[120:123], s[8:9]
	s_waitcnt lgkmcnt(0)
	v_mul_f32_e32 v244, v112, v55
	v_mul_f32_e32 v245, v113, v55
	v_mul_f32_e32 v246, v114, v55
	v_mul_f32_e32 v247, v115, v55
	v_mul_f32_e32 v248, v116, v55
	v_mul_f32_e32 v249, v117, v55
	v_mul_f32_e32 v250, v118, v55
	v_mul_f32_e32 v251, v119, v55
	v_cvt_pk_bf16_f32 v124, v244, v245
	v_cvt_pk_bf16_f32 v125, v246, v247
	v_cvt_pk_bf16_f32 v126, v248, v249
	v_cvt_pk_bf16_f32 v127, v250, v251
	v_mul_u32_u24_e32 v49, 0x420, v46
	v_lshl_add_u32 v49, v47, 4, v49
	v_mul_u32_u24_e32 v50, 0x120, v46
	v_lshl_add_u32 v50, v47, 4, v50
	v_add_u32_e32 v50, 0x10400, v50
	v_cmp_gt_u32_e32 vcc, 64, v47
	s_nop 1
	v_cndmask_b32_e32 v49, v50, v49, vcc
	v_cndmask_b32_e32 v124, v120, v124, vcc
	v_cndmask_b32_e32 v125, v121, v125, vcc
	v_cndmask_b32_e32 v126, v122, v126, vcc
	v_cndmask_b32_e32 v127, v123, v127, vcc
	v_cmp_gt_u32_e32 vcc, 80, v47
	s_and_saveexec_b64 s[12:13], vcc
	ds_write_b128 v49, v[124:127]
	s_or_b64 exec, exec, s[12:13]
	v_add_u32_e32 v49, 2560, v166
	v_mul_hi_i32 v46, v49, s67
	v_ashrrev_i32_e32 v46, 4, v46
	v_mul_lo_u32 v50, v46, s52
	v_sub_u32_e32 v47, v49, v50
	v_lshl_add_u32 v48, v47, 3, s71
	v_cmp_lt_u32_e32 vcc, 63, v47
	s_nop 1
	v_cndmask_b32_e64 v50, 0, 1, vcc
	v_mad_u32_u24 v48, v50, v42, v48
	v_cmp_lt_u32_e32 vcc, 79, v47
	s_nop 1
	v_cndmask_b32_e64 v50, 0, 1, vcc
	v_lshl_add_u32 v48, v50, 7, v48
	v_lshlrev_b32_e32 v50, 2, v48
	global_load_dwordx4 v[112:115], v50, s[78:79]
	global_load_dwordx4 v[116:119], v50, s[78:79] offset:16
	v_mul_u32_u24_e32 v51, 0x3600, v46
	v_lshl_add_u32 v51, v48, 1, v51
	s_add_u32 s4, s6, 0xffff8600
	s_addc_u32 s5, s7, -1
	global_load_dwordx4 v[120:123], v51, s[4:5]
	s_add_u32 s4, s6, 0xffffbc00
	s_addc_u32 s5, s7, -1
	global_load_dwordx4 v[124:127], v51, s[4:5]
	s_add_u32 s4, s6, 0xfffff200
	s_addc_u32 s5, s7, -1
	global_load_dwordx4 v[128:131], v51, s[4:5]
	s_add_u32 s4, s6, 0x2800
	s_addc_u32 s5, s7, 0
	global_load_dwordx4 v[132:135], v51, s[4:5]
	global_load_dwordx4 v[136:139], v50, s[92:93]
	global_load_dwordx4 v[140:143], v50, s[92:93] offset:16
	s_add_u32 s4, s92, 0x1800
	s_addc_u32 s5, s93, 0
	global_load_dwordx4 v[144:147], v50, s[4:5]
	global_load_dwordx4 v[148:151], v50, s[4:5] offset:16
	s_add_u32 s4, s92, 0x3000
	s_addc_u32 s5, s93, 0
	global_load_dwordx4 v[152:155], v50, s[4:5]
	global_load_dwordx4 v[156:159], v50, s[4:5] offset:16
	s_add_u32 s4, s92, 0x4800
	s_addc_u32 s5, s93, 0
	global_load_dwordx4 v[160:163], v50, s[4:5]
	global_load_dwordx4 v[252:255], v50, s[4:5] offset:16
	s_waitcnt vmcnt(15)
	v_lshrrev_b32_e32 v49, 3, v44
	v_lshl_add_u32 v49, v49, 6, v43
	v_lshlrev_b32_e32 v49, 2, v49
	v_add_u32_e32 v49, 0x15000, v49
	ds_read_b32 v55, v49
	s_cmp_eq_u32 s68, 0
	s_cbranch_scc0 .Lsc_nomask_4
	v_cmp_gt_u32_e32 vcc, 3, v43
	s_nop 1
	v_cndmask_b32_e64 v64, v64, 0, vcc
	v_cndmask_b32_e64 v65, v65, 0, vcc
	v_cndmask_b32_e64 v66, v66, 0, vcc
	v_cndmask_b32_e64 v67, v67, 0, vcc
	v_cmp_gt_u32_e32 vcc, 2, v43
	s_nop 1
	v_cndmask_b32_e64 v68, v68, 0, vcc
	v_cndmask_b32_e64 v69, v69, 0, vcc
	v_cndmask_b32_e64 v70, v70, 0, vcc
	v_cndmask_b32_e64 v71, v71, 0, vcc
	v_cmp_gt_u32_e32 vcc, 1, v43
	s_nop 1
	v_cndmask_b32_e64 v72, v72, 0, vcc
	v_cndmask_b32_e64 v73, v73, 0, vcc
	v_cndmask_b32_e64 v74, v74, 0, vcc
	v_cndmask_b32_e64 v75, v75, 0, vcc
.Lsc_nomask_4:
	v_lshlrev_b32_e32 v49, 16, v64
	v_and_b32_e32 v64, 0xffff0000, v64
	v_fmac_f32_e32 v56, v80, v49
	v_fmac_f32_e32 v57, v81, v64
	v_lshlrev_b32_e32 v49, 16, v65
	v_and_b32_e32 v65, 0xffff0000, v65
	v_fmac_f32_e32 v58, v82, v49
	v_fmac_f32_e32 v59, v83, v65
	v_lshlrev_b32_e32 v49, 16, v66
	v_and_b32_e32 v66, 0xffff0000, v66
	v_fmac_f32_e32 v60, v84, v49
	v_fmac_f32_e32 v61, v85, v66
	v_lshlrev_b32_e32 v49, 16, v67
	v_and_b32_e32 v67, 0xffff0000, v67
	v_fmac_f32_e32 v62, v86, v49
	v_fmac_f32_e32 v63, v87, v67
	v_lshlrev_b32_e32 v49, 16, v68
	v_and_b32_e32 v68, 0xffff0000, v68
	v_fmac_f32_e32 v56, v88, v49
	v_fmac_f32_e32 v57, v89, v68
	v_lshlrev_b32_e32 v49, 16, v69
	v_and_b32_e32 v69, 0xffff0000, v69
	v_fmac_f32_e32 v58, v90, v49
	v_fmac_f32_e32 v59, v91, v69
	v_lshlrev_b32_e32 v49, 16, v70
	v_and_b32_e32 v70, 0xffff0000, v70
	v_fmac_f32_e32 v60, v92, v49
	v_fmac_f32_e32 v61, v93, v70
	v_lshlrev_b32_e32 v49, 16, v71
	v_and_b32_e32 v71, 0xffff0000, v71
	v_fmac_f32_e32 v62, v94, v49
	v_fmac_f32_e32 v63, v95, v71
	v_lshlrev_b32_e32 v49, 16, v72
	v_and_b32_e32 v72, 0xffff0000, v72
	v_fmac_f32_e32 v56, v96, v49
	v_fmac_f32_e32 v57, v97, v72
	v_lshlrev_b32_e32 v49, 16, v73
	v_and_b32_e32 v73, 0xffff0000, v73
	v_fmac_f32_e32 v58, v98, v49
	v_fmac_f32_e32 v59, v99, v73
	v_lshlrev_b32_e32 v49, 16, v74
	v_and_b32_e32 v74, 0xffff0000, v74
	v_fmac_f32_e32 v60, v100, v49
	v_fmac_f32_e32 v61, v101, v74
	v_lshlrev_b32_e32 v49, 16, v75
	v_and_b32_e32 v75, 0xffff0000, v75
	v_fmac_f32_e32 v62, v102, v49
	v_fmac_f32_e32 v63, v103, v75
	v_lshlrev_b32_e32 v49, 16, v76
	v_and_b32_e32 v76, 0xffff0000, v76
	v_fmac_f32_e32 v56, v104, v49
	v_fmac_f32_e32 v57, v105, v76
	v_lshlrev_b32_e32 v49, 16, v77
	v_and_b32_e32 v77, 0xffff0000, v77
	v_fmac_f32_e32 v58, v106, v49
	v_fmac_f32_e32 v59, v107, v77
	v_lshlrev_b32_e32 v49, 16, v78
	v_and_b32_e32 v78, 0xffff0000, v78
	v_fmac_f32_e32 v60, v108, v49
	v_fmac_f32_e32 v61, v109, v78
	v_lshlrev_b32_e32 v49, 16, v79
	v_and_b32_e32 v79, 0xffff0000, v79
	v_fmac_f32_e32 v62, v110, v49
	v_fmac_f32_e32 v63, v111, v79
	v_mul_f32_e32 v49, 0xbfb8aa3b, v56
	v_mul_f32_e32 v50, 0xbfb8aa3b, v57
	v_exp_f32_e32 v49, v49
	v_exp_f32_e32 v50, v50
	v_add_f32_e32 v49, 1.0, v49
	v_add_f32_e32 v50, 1.0, v50
	v_rcp_f32_e32 v49, v49
	v_rcp_f32_e32 v50, v50
	v_mul_f32_e32 v56, v56, v49
	v_mul_f32_e32 v57, v57, v50
	v_mul_f32_e32 v49, 0xbfb8aa3b, v58
	v_mul_f32_e32 v50, 0xbfb8aa3b, v59
	v_exp_f32_e32 v49, v49
	v_exp_f32_e32 v50, v50
	v_add_f32_e32 v49, 1.0, v49
	v_add_f32_e32 v50, 1.0, v50
	v_rcp_f32_e32 v49, v49
	v_rcp_f32_e32 v50, v50
	v_mul_f32_e32 v58, v58, v49
	v_mul_f32_e32 v59, v59, v50
	v_mul_f32_e32 v49, 0xbfb8aa3b, v60
	v_mul_f32_e32 v50, 0xbfb8aa3b, v61
	v_exp_f32_e32 v49, v49
	v_exp_f32_e32 v50, v50
	v_add_f32_e32 v49, 1.0, v49
	v_add_f32_e32 v50, 1.0, v50
	v_rcp_f32_e32 v49, v49
	v_rcp_f32_e32 v50, v50
	v_mul_f32_e32 v60, v60, v49
	v_mul_f32_e32 v61, v61, v50
	v_mul_f32_e32 v49, 0xbfb8aa3b, v62
	v_mul_f32_e32 v50, 0xbfb8aa3b, v63
	v_exp_f32_e32 v49, v49
	v_exp_f32_e32 v50, v50
	v_add_f32_e32 v49, 1.0, v49
	v_add_f32_e32 v50, 1.0, v50
	v_rcp_f32_e32 v49, v49
	v_rcp_f32_e32 v50, v50
	v_mul_f32_e32 v62, v62, v49
	v_mul_f32_e32 v63, v63, v50
	v_cvt_pk_bf16_f32 v64, v56, v57
	v_cvt_pk_bf16_f32 v65, v58, v59
	v_cvt_pk_bf16_f32 v66, v60, v61
	v_cvt_pk_bf16_f32 v67, v62, v63
	v_mul_u32_u24_e32 v49, 0xc00, v43
	v_lshl_add_u32 v49, v45, 1, v49
	global_store_dwordx4 v49, v[64:67], s[8:9]
	s_waitcnt lgkmcnt(0)
	v_mul_f32_e32 v244, v56, v55
	v_mul_f32_e32 v245, v57, v55
	v_mul_f32_e32 v246, v58, v55
	v_mul_f32_e32 v247, v59, v55
	v_mul_f32_e32 v248, v60, v55
	v_mul_f32_e32 v249, v61, v55
	v_mul_f32_e32 v250, v62, v55
	v_mul_f32_e32 v251, v63, v55
	v_cvt_pk_bf16_f32 v68, v244, v245
	v_cvt_pk_bf16_f32 v69, v246, v247
	v_cvt_pk_bf16_f32 v70, v248, v249
	v_cvt_pk_bf16_f32 v71, v250, v251
	v_mul_u32_u24_e32 v49, 0x420, v43
	v_lshl_add_u32 v49, v44, 4, v49
	v_mul_u32_u24_e32 v50, 0x120, v43
	v_lshl_add_u32 v50, v44, 4, v50
	v_add_u32_e32 v50, 0x10400, v50
	v_cmp_gt_u32_e32 vcc, 64, v44
	s_nop 1
	v_cndmask_b32_e32 v49, v50, v49, vcc
	v_cndmask_b32_e32 v68, v64, v68, vcc
	v_cndmask_b32_e32 v69, v65, v69, vcc
	v_cndmask_b32_e32 v70, v66, v70, vcc
	v_cndmask_b32_e32 v71, v67, v71, vcc
	v_cmp_gt_u32_e32 vcc, 80, v44
	s_and_saveexec_b64 s[12:13], vcc
	ds_write_b128 v49, v[68:71]
	s_or_b64 exec, exec, s[12:13]
	v_add_u32_e32 v49, 3072, v166
	v_mul_hi_i32 v43, v49, s67
	v_ashrrev_i32_e32 v43, 4, v43
	v_mul_lo_u32 v50, v43, s52
	v_sub_u32_e32 v44, v49, v50
	v_lshl_add_u32 v45, v44, 3, s71
	v_cmp_lt_u32_e32 vcc, 63, v44
	s_nop 1
	v_cndmask_b32_e64 v50, 0, 1, vcc
	v_mad_u32_u24 v45, v50, v42, v45
	v_cmp_lt_u32_e32 vcc, 79, v44
	s_nop 1
	v_cndmask_b32_e64 v50, 0, 1, vcc
	v_lshl_add_u32 v45, v50, 7, v45
	v_lshlrev_b32_e32 v50, 2, v45
	global_load_dwordx4 v[56:59], v50, s[78:79]
	global_load_dwordx4 v[60:63], v50, s[78:79] offset:16
	v_mul_u32_u24_e32 v51, 0x3600, v43
	v_lshl_add_u32 v51, v45, 1, v51
	s_add_u32 s4, s6, 0xffff8600
	s_addc_u32 s5, s7, -1
	global_load_dwordx4 v[64:67], v51, s[4:5]
	s_add_u32 s4, s6, 0xffffbc00
	s_addc_u32 s5, s7, -1
	global_load_dwordx4 v[68:71], v51, s[4:5]
	s_add_u32 s4, s6, 0xfffff200
	s_addc_u32 s5, s7, -1
	global_load_dwordx4 v[72:75], v51, s[4:5]
	s_add_u32 s4, s6, 0x2800
	s_addc_u32 s5, s7, 0
	global_load_dwordx4 v[76:79], v51, s[4:5]
	global_load_dwordx4 v[80:83], v50, s[92:93]
	global_load_dwordx4 v[84:87], v50, s[92:93] offset:16
	s_add_u32 s4, s92, 0x1800
	s_addc_u32 s5, s93, 0
	global_load_dwordx4 v[88:91], v50, s[4:5]
	global_load_dwordx4 v[92:95], v50, s[4:5] offset:16
	s_add_u32 s4, s92, 0x3000
	s_addc_u32 s5, s93, 0
	global_load_dwordx4 v[96:99], v50, s[4:5]
	global_load_dwordx4 v[100:103], v50, s[4:5] offset:16
	s_add_u32 s4, s92, 0x4800
	s_addc_u32 s5, s93, 0
	global_load_dwordx4 v[104:107], v50, s[4:5]
	global_load_dwordx4 v[108:111], v50, s[4:5] offset:16
	s_waitcnt vmcnt(15)
	v_lshrrev_b32_e32 v49, 3, v47
	v_lshl_add_u32 v49, v49, 6, v46
	v_lshlrev_b32_e32 v49, 2, v49
	v_add_u32_e32 v49, 0x15000, v49
	ds_read_b32 v55, v49
	s_cmp_eq_u32 s68, 0
	s_cbranch_scc0 .Lsc_nomask_5
	v_cmp_gt_u32_e32 vcc, 3, v46
	s_nop 1
	v_cndmask_b32_e64 v120, v120, 0, vcc
	v_cndmask_b32_e64 v121, v121, 0, vcc
	v_cndmask_b32_e64 v122, v122, 0, vcc
	v_cndmask_b32_e64 v123, v123, 0, vcc
	v_cmp_gt_u32_e32 vcc, 2, v46
	s_nop 1
	v_cndmask_b32_e64 v124, v124, 0, vcc
	v_cndmask_b32_e64 v125, v125, 0, vcc
	v_cndmask_b32_e64 v126, v126, 0, vcc
	v_cndmask_b32_e64 v127, v127, 0, vcc
	v_cmp_gt_u32_e32 vcc, 1, v46
	s_nop 1
	v_cndmask_b32_e64 v128, v128, 0, vcc
	v_cndmask_b32_e64 v129, v129, 0, vcc
	v_cndmask_b32_e64 v130, v130, 0, vcc
	v_cndmask_b32_e64 v131, v131, 0, vcc
.Lsc_nomask_5:
	v_lshlrev_b32_e32 v49, 16, v120
	v_and_b32_e32 v120, 0xffff0000, v120
	v_fmac_f32_e32 v112, v136, v49
	v_fmac_f32_e32 v113, v137, v120
	v_lshlrev_b32_e32 v49, 16, v121
	v_and_b32_e32 v121, 0xffff0000, v121
	v_fmac_f32_e32 v114, v138, v49
	v_fmac_f32_e32 v115, v139, v121
	v_lshlrev_b32_e32 v49, 16, v122
	v_and_b32_e32 v122, 0xffff0000, v122
	v_fmac_f32_e32 v116, v140, v49
	v_fmac_f32_e32 v117, v141, v122
	v_lshlrev_b32_e32 v49, 16, v123
	v_and_b32_e32 v123, 0xffff0000, v123
	v_fmac_f32_e32 v118, v142, v49
	v_fmac_f32_e32 v119, v143, v123
	v_lshlrev_b32_e32 v49, 16, v124
	v_and_b32_e32 v124, 0xffff0000, v124
	v_fmac_f32_e32 v112, v144, v49
	v_fmac_f32_e32 v113, v145, v124
	v_lshlrev_b32_e32 v49, 16, v125
	v_and_b32_e32 v125, 0xffff0000, v125
	v_fmac_f32_e32 v114, v146, v49
	v_fmac_f32_e32 v115, v147, v125
	v_lshlrev_b32_e32 v49, 16, v126
	v_and_b32_e32 v126, 0xffff0000, v126
	v_fmac_f32_e32 v116, v148, v49
	v_fmac_f32_e32 v117, v149, v126
	v_lshlrev_b32_e32 v49, 16, v127
	v_and_b32_e32 v127, 0xffff0000, v127
	v_fmac_f32_e32 v118, v150, v49
	v_fmac_f32_e32 v119, v151, v127
	v_lshlrev_b32_e32 v49, 16, v128
	v_and_b32_e32 v128, 0xffff0000, v128
	v_fmac_f32_e32 v112, v152, v49
	v_fmac_f32_e32 v113, v153, v128
	v_lshlrev_b32_e32 v49, 16, v129
	v_and_b32_e32 v129, 0xffff0000, v129
	v_fmac_f32_e32 v114, v154, v49
	v_fmac_f32_e32 v115, v155, v129
	v_lshlrev_b32_e32 v49, 16, v130
	v_and_b32_e32 v130, 0xffff0000, v130
	v_fmac_f32_e32 v116, v156, v49
	v_fmac_f32_e32 v117, v157, v130
	v_lshlrev_b32_e32 v49, 16, v131
	v_and_b32_e32 v131, 0xffff0000, v131
	v_fmac_f32_e32 v118, v158, v49
	v_fmac_f32_e32 v119, v159, v131
	v_lshlrev_b32_e32 v49, 16, v132
	v_and_b32_e32 v132, 0xffff0000, v132
	v_fmac_f32_e32 v112, v160, v49
	v_fmac_f32_e32 v113, v161, v132
	v_lshlrev_b32_e32 v49, 16, v133
	v_and_b32_e32 v133, 0xffff0000, v133
	v_fmac_f32_e32 v114, v162, v49
	v_fmac_f32_e32 v115, v163, v133
	v_lshlrev_b32_e32 v49, 16, v134
	v_and_b32_e32 v134, 0xffff0000, v134
	v_fmac_f32_e32 v116, v252, v49
	v_fmac_f32_e32 v117, v253, v134
	v_lshlrev_b32_e32 v49, 16, v135
	v_and_b32_e32 v135, 0xffff0000, v135
	v_fmac_f32_e32 v118, v254, v49
	v_fmac_f32_e32 v119, v255, v135
	v_mul_f32_e32 v49, 0xbfb8aa3b, v112
	v_mul_f32_e32 v50, 0xbfb8aa3b, v113
	v_exp_f32_e32 v49, v49
	v_exp_f32_e32 v50, v50
	v_add_f32_e32 v49, 1.0, v49
	v_add_f32_e32 v50, 1.0, v50
	v_rcp_f32_e32 v49, v49
	v_rcp_f32_e32 v50, v50
	v_mul_f32_e32 v112, v112, v49
	v_mul_f32_e32 v113, v113, v50
	v_mul_f32_e32 v49, 0xbfb8aa3b, v114
	v_mul_f32_e32 v50, 0xbfb8aa3b, v115
	v_exp_f32_e32 v49, v49
	v_exp_f32_e32 v50, v50
	v_add_f32_e32 v49, 1.0, v49
	v_add_f32_e32 v50, 1.0, v50
	v_rcp_f32_e32 v49, v49
	v_rcp_f32_e32 v50, v50
	v_mul_f32_e32 v114, v114, v49
	v_mul_f32_e32 v115, v115, v50
	v_mul_f32_e32 v49, 0xbfb8aa3b, v116
	v_mul_f32_e32 v50, 0xbfb8aa3b, v117
	v_exp_f32_e32 v49, v49
	v_exp_f32_e32 v50, v50
	v_add_f32_e32 v49, 1.0, v49
	v_add_f32_e32 v50, 1.0, v50
	v_rcp_f32_e32 v49, v49
	v_rcp_f32_e32 v50, v50
	v_mul_f32_e32 v116, v116, v49
	v_mul_f32_e32 v117, v117, v50
	v_mul_f32_e32 v49, 0xbfb8aa3b, v118
	v_mul_f32_e32 v50, 0xbfb8aa3b, v119
	v_exp_f32_e32 v49, v49
	v_exp_f32_e32 v50, v50
	v_add_f32_e32 v49, 1.0, v49
	v_add_f32_e32 v50, 1.0, v50
	v_rcp_f32_e32 v49, v49
	v_rcp_f32_e32 v50, v50
	v_mul_f32_e32 v118, v118, v49
	v_mul_f32_e32 v119, v119, v50
	v_cvt_pk_bf16_f32 v120, v112, v113
	v_cvt_pk_bf16_f32 v121, v114, v115
	v_cvt_pk_bf16_f32 v122, v116, v117
	v_cvt_pk_bf16_f32 v123, v118, v119
	v_mul_u32_u24_e32 v49, 0xc00, v46
	v_lshl_add_u32 v49, v48, 1, v49
	global_store_dwordx4 v49, v[120:123], s[8:9]
	s_waitcnt lgkmcnt(0)
	v_mul_f32_e32 v244, v112, v55
	v_mul_f32_e32 v245, v113, v55
	v_mul_f32_e32 v246, v114, v55
	v_mul_f32_e32 v247, v115, v55
	v_mul_f32_e32 v248, v116, v55
	v_mul_f32_e32 v249, v117, v55
	v_mul_f32_e32 v250, v118, v55
	v_mul_f32_e32 v251, v119, v55
	v_cvt_pk_bf16_f32 v124, v244, v245
	v_cvt_pk_bf16_f32 v125, v246, v247
	v_cvt_pk_bf16_f32 v126, v248, v249
	v_cvt_pk_bf16_f32 v127, v250, v251
	v_mul_u32_u24_e32 v49, 0x420, v46
	v_lshl_add_u32 v49, v47, 4, v49
	v_mul_u32_u24_e32 v50, 0x120, v46
	v_lshl_add_u32 v50, v47, 4, v50
	v_add_u32_e32 v50, 0x10400, v50
	v_cmp_gt_u32_e32 vcc, 64, v47
	s_nop 1
	v_cndmask_b32_e32 v49, v50, v49, vcc
	v_cndmask_b32_e32 v124, v120, v124, vcc
	v_cndmask_b32_e32 v125, v121, v125, vcc
	v_cndmask_b32_e32 v126, v122, v126, vcc
	v_cndmask_b32_e32 v127, v123, v127, vcc
	v_cmp_gt_u32_e32 vcc, 80, v47
	s_and_saveexec_b64 s[12:13], vcc
	ds_write_b128 v49, v[124:127]
	s_or_b64 exec, exec, s[12:13]
	v_add_u32_e32 v49, 3584, v166
	v_mul_hi_i32 v46, v49, s67
	v_ashrrev_i32_e32 v46, 4, v46
	v_mul_lo_u32 v50, v46, s52
	v_sub_u32_e32 v47, v49, v50
	v_lshl_add_u32 v48, v47, 3, s71
	v_cmp_lt_u32_e32 vcc, 63, v47
	s_nop 1
	v_cndmask_b32_e64 v50, 0, 1, vcc
	v_mad_u32_u24 v48, v50, v42, v48
	v_cmp_lt_u32_e32 vcc, 79, v47
	s_nop 1
	v_cndmask_b32_e64 v50, 0, 1, vcc
	v_lshl_add_u32 v48, v50, 7, v48
	v_lshlrev_b32_e32 v50, 2, v48
	global_load_dwordx4 v[112:115], v50, s[78:79]
	global_load_dwordx4 v[116:119], v50, s[78:79] offset:16
	v_mul_u32_u24_e32 v51, 0x3600, v46
	v_lshl_add_u32 v51, v48, 1, v51
	s_add_u32 s4, s6, 0xffff8600
	s_addc_u32 s5, s7, -1
	global_load_dwordx4 v[120:123], v51, s[4:5]
	s_add_u32 s4, s6, 0xffffbc00
	s_addc_u32 s5, s7, -1
	global_load_dwordx4 v[124:127], v51, s[4:5]
	s_add_u32 s4, s6, 0xfffff200
	s_addc_u32 s5, s7, -1
	global_load_dwordx4 v[128:131], v51, s[4:5]
	s_add_u32 s4, s6, 0x2800
	s_addc_u32 s5, s7, 0
	global_load_dwordx4 v[132:135], v51, s[4:5]
	global_load_dwordx4 v[136:139], v50, s[92:93]
	global_load_dwordx4 v[140:143], v50, s[92:93] offset:16
	s_add_u32 s4, s92, 0x1800
	s_addc_u32 s5, s93, 0
	global_load_dwordx4 v[144:147], v50, s[4:5]
	global_load_dwordx4 v[148:151], v50, s[4:5] offset:16
	s_add_u32 s4, s92, 0x3000
	s_addc_u32 s5, s93, 0
	global_load_dwordx4 v[152:155], v50, s[4:5]
	global_load_dwordx4 v[156:159], v50, s[4:5] offset:16
	s_add_u32 s4, s92, 0x4800
	s_addc_u32 s5, s93, 0
	global_load_dwordx4 v[160:163], v50, s[4:5]
	global_load_dwordx4 v[252:255], v50, s[4:5] offset:16
	s_waitcnt vmcnt(15)
	v_lshrrev_b32_e32 v49, 3, v44
	v_lshl_add_u32 v49, v49, 6, v43
	v_lshlrev_b32_e32 v49, 2, v49
	v_add_u32_e32 v49, 0x15000, v49
	ds_read_b32 v55, v49
	s_cmp_eq_u32 s68, 0
	s_cbranch_scc0 .Lsc_nomask_6
	v_cmp_gt_u32_e32 vcc, 3, v43
	s_nop 1
	v_cndmask_b32_e64 v64, v64, 0, vcc
	v_cndmask_b32_e64 v65, v65, 0, vcc
	v_cndmask_b32_e64 v66, v66, 0, vcc
	v_cndmask_b32_e64 v67, v67, 0, vcc
	v_cmp_gt_u32_e32 vcc, 2, v43
	s_nop 1
	v_cndmask_b32_e64 v68, v68, 0, vcc
	v_cndmask_b32_e64 v69, v69, 0, vcc
	v_cndmask_b32_e64 v70, v70, 0, vcc
	v_cndmask_b32_e64 v71, v71, 0, vcc
	v_cmp_gt_u32_e32 vcc, 1, v43
	s_nop 1
	v_cndmask_b32_e64 v72, v72, 0, vcc
	v_cndmask_b32_e64 v73, v73, 0, vcc
	v_cndmask_b32_e64 v74, v74, 0, vcc
	v_cndmask_b32_e64 v75, v75, 0, vcc
.Lsc_nomask_6:
	v_lshlrev_b32_e32 v49, 16, v64
	v_and_b32_e32 v64, 0xffff0000, v64
	v_fmac_f32_e32 v56, v80, v49
	v_fmac_f32_e32 v57, v81, v64
	v_lshlrev_b32_e32 v49, 16, v65
	v_and_b32_e32 v65, 0xffff0000, v65
	v_fmac_f32_e32 v58, v82, v49
	v_fmac_f32_e32 v59, v83, v65
	v_lshlrev_b32_e32 v49, 16, v66
	v_and_b32_e32 v66, 0xffff0000, v66
	v_fmac_f32_e32 v60, v84, v49
	v_fmac_f32_e32 v61, v85, v66
	v_lshlrev_b32_e32 v49, 16, v67
	v_and_b32_e32 v67, 0xffff0000, v67
	v_fmac_f32_e32 v62, v86, v49
	v_fmac_f32_e32 v63, v87, v67
	v_lshlrev_b32_e32 v49, 16, v68
	v_and_b32_e32 v68, 0xffff0000, v68
	v_fmac_f32_e32 v56, v88, v49
	v_fmac_f32_e32 v57, v89, v68
	v_lshlrev_b32_e32 v49, 16, v69
	v_and_b32_e32 v69, 0xffff0000, v69
	v_fmac_f32_e32 v58, v90, v49
	v_fmac_f32_e32 v59, v91, v69
	v_lshlrev_b32_e32 v49, 16, v70
	v_and_b32_e32 v70, 0xffff0000, v70
	v_fmac_f32_e32 v60, v92, v49
	v_fmac_f32_e32 v61, v93, v70
	v_lshlrev_b32_e32 v49, 16, v71
	v_and_b32_e32 v71, 0xffff0000, v71
	v_fmac_f32_e32 v62, v94, v49
	v_fmac_f32_e32 v63, v95, v71
	v_lshlrev_b32_e32 v49, 16, v72
	v_and_b32_e32 v72, 0xffff0000, v72
	v_fmac_f32_e32 v56, v96, v49
	v_fmac_f32_e32 v57, v97, v72
	v_lshlrev_b32_e32 v49, 16, v73
	v_and_b32_e32 v73, 0xffff0000, v73
	v_fmac_f32_e32 v58, v98, v49
	v_fmac_f32_e32 v59, v99, v73
	v_lshlrev_b32_e32 v49, 16, v74
	v_and_b32_e32 v74, 0xffff0000, v74
	v_fmac_f32_e32 v60, v100, v49
	v_fmac_f32_e32 v61, v101, v74
	v_lshlrev_b32_e32 v49, 16, v75
	v_and_b32_e32 v75, 0xffff0000, v75
	v_fmac_f32_e32 v62, v102, v49
	v_fmac_f32_e32 v63, v103, v75
	v_lshlrev_b32_e32 v49, 16, v76
	v_and_b32_e32 v76, 0xffff0000, v76
	v_fmac_f32_e32 v56, v104, v49
	v_fmac_f32_e32 v57, v105, v76
	v_lshlrev_b32_e32 v49, 16, v77
	v_and_b32_e32 v77, 0xffff0000, v77
	v_fmac_f32_e32 v58, v106, v49
	v_fmac_f32_e32 v59, v107, v77
	v_lshlrev_b32_e32 v49, 16, v78
	v_and_b32_e32 v78, 0xffff0000, v78
	v_fmac_f32_e32 v60, v108, v49
	v_fmac_f32_e32 v61, v109, v78
	v_lshlrev_b32_e32 v49, 16, v79
	v_and_b32_e32 v79, 0xffff0000, v79
	v_fmac_f32_e32 v62, v110, v49
	v_fmac_f32_e32 v63, v111, v79
	v_mul_f32_e32 v49, 0xbfb8aa3b, v56
	v_mul_f32_e32 v50, 0xbfb8aa3b, v57
	v_exp_f32_e32 v49, v49
	v_exp_f32_e32 v50, v50
	v_add_f32_e32 v49, 1.0, v49
	v_add_f32_e32 v50, 1.0, v50
	v_rcp_f32_e32 v49, v49
	v_rcp_f32_e32 v50, v50
	v_mul_f32_e32 v56, v56, v49
	v_mul_f32_e32 v57, v57, v50
	v_mul_f32_e32 v49, 0xbfb8aa3b, v58
	v_mul_f32_e32 v50, 0xbfb8aa3b, v59
	v_exp_f32_e32 v49, v49
	v_exp_f32_e32 v50, v50
	v_add_f32_e32 v49, 1.0, v49
	v_add_f32_e32 v50, 1.0, v50
	v_rcp_f32_e32 v49, v49
	v_rcp_f32_e32 v50, v50
	v_mul_f32_e32 v58, v58, v49
	v_mul_f32_e32 v59, v59, v50
	v_mul_f32_e32 v49, 0xbfb8aa3b, v60
	v_mul_f32_e32 v50, 0xbfb8aa3b, v61
	v_exp_f32_e32 v49, v49
	v_exp_f32_e32 v50, v50
	v_add_f32_e32 v49, 1.0, v49
	v_add_f32_e32 v50, 1.0, v50
	v_rcp_f32_e32 v49, v49
	v_rcp_f32_e32 v50, v50
	v_mul_f32_e32 v60, v60, v49
	v_mul_f32_e32 v61, v61, v50
	v_mul_f32_e32 v49, 0xbfb8aa3b, v62
	v_mul_f32_e32 v50, 0xbfb8aa3b, v63
	v_exp_f32_e32 v49, v49
	v_exp_f32_e32 v50, v50
	v_add_f32_e32 v49, 1.0, v49
	v_add_f32_e32 v50, 1.0, v50
	v_rcp_f32_e32 v49, v49
	v_rcp_f32_e32 v50, v50
	v_mul_f32_e32 v62, v62, v49
	v_mul_f32_e32 v63, v63, v50
	v_cvt_pk_bf16_f32 v64, v56, v57
	v_cvt_pk_bf16_f32 v65, v58, v59
	v_cvt_pk_bf16_f32 v66, v60, v61
	v_cvt_pk_bf16_f32 v67, v62, v63
	v_mul_u32_u24_e32 v49, 0xc00, v43
	v_lshl_add_u32 v49, v45, 1, v49
	global_store_dwordx4 v49, v[64:67], s[8:9]
	s_waitcnt lgkmcnt(0)
	v_mul_f32_e32 v244, v56, v55
	v_mul_f32_e32 v245, v57, v55
	v_mul_f32_e32 v246, v58, v55
	v_mul_f32_e32 v247, v59, v55
	v_mul_f32_e32 v248, v60, v55
	v_mul_f32_e32 v249, v61, v55
	v_mul_f32_e32 v250, v62, v55
	v_mul_f32_e32 v251, v63, v55
	v_cvt_pk_bf16_f32 v68, v244, v245
	v_cvt_pk_bf16_f32 v69, v246, v247
	v_cvt_pk_bf16_f32 v70, v248, v249
	v_cvt_pk_bf16_f32 v71, v250, v251
	v_mul_u32_u24_e32 v49, 0x420, v43
	v_lshl_add_u32 v49, v44, 4, v49
	v_mul_u32_u24_e32 v50, 0x120, v43
	v_lshl_add_u32 v50, v44, 4, v50
	v_add_u32_e32 v50, 0x10400, v50
	v_cmp_gt_u32_e32 vcc, 64, v44
	s_nop 1
	v_cndmask_b32_e32 v49, v50, v49, vcc
	v_cndmask_b32_e32 v68, v64, v68, vcc
	v_cndmask_b32_e32 v69, v65, v69, vcc
	v_cndmask_b32_e32 v70, v66, v70, vcc
	v_cndmask_b32_e32 v71, v67, v71, vcc
	v_cmp_gt_u32_e32 vcc, 80, v44
	s_and_saveexec_b64 s[12:13], vcc
	ds_write_b128 v49, v[68:71]
	s_or_b64 exec, exec, s[12:13]
	v_add_u32_e32 v49, 4096, v166
	v_mul_hi_i32 v43, v49, s67
	v_ashrrev_i32_e32 v43, 4, v43
	v_mul_lo_u32 v50, v43, s52
	v_sub_u32_e32 v44, v49, v50
	v_lshl_add_u32 v45, v44, 3, s71
	v_cmp_lt_u32_e32 vcc, 63, v44
	s_nop 1
	v_cndmask_b32_e64 v50, 0, 1, vcc
	v_mad_u32_u24 v45, v50, v42, v45
	v_cmp_lt_u32_e32 vcc, 79, v44
	s_nop 1
	v_cndmask_b32_e64 v50, 0, 1, vcc
	v_lshl_add_u32 v45, v50, 7, v45
	v_lshlrev_b32_e32 v50, 2, v45
	global_load_dwordx4 v[56:59], v50, s[78:79]
	global_load_dwordx4 v[60:63], v50, s[78:79] offset:16
	v_mul_u32_u24_e32 v51, 0x3600, v43
	v_lshl_add_u32 v51, v45, 1, v51
	s_add_u32 s4, s6, 0xffff8600
	s_addc_u32 s5, s7, -1
	global_load_dwordx4 v[64:67], v51, s[4:5]
	s_add_u32 s4, s6, 0xffffbc00
	s_addc_u32 s5, s7, -1
	global_load_dwordx4 v[68:71], v51, s[4:5]
	s_add_u32 s4, s6, 0xfffff200
	s_addc_u32 s5, s7, -1
	global_load_dwordx4 v[72:75], v51, s[4:5]
	s_add_u32 s4, s6, 0x2800
	s_addc_u32 s5, s7, 0
	global_load_dwordx4 v[76:79], v51, s[4:5]
	global_load_dwordx4 v[80:83], v50, s[92:93]
	global_load_dwordx4 v[84:87], v50, s[92:93] offset:16
	s_add_u32 s4, s92, 0x1800
	s_addc_u32 s5, s93, 0
	global_load_dwordx4 v[88:91], v50, s[4:5]
	global_load_dwordx4 v[92:95], v50, s[4:5] offset:16
	s_add_u32 s4, s92, 0x3000
	s_addc_u32 s5, s93, 0
	global_load_dwordx4 v[96:99], v50, s[4:5]
	global_load_dwordx4 v[100:103], v50, s[4:5] offset:16
	s_add_u32 s4, s92, 0x4800
	s_addc_u32 s5, s93, 0
	global_load_dwordx4 v[104:107], v50, s[4:5]
	global_load_dwordx4 v[108:111], v50, s[4:5] offset:16
	s_waitcnt vmcnt(15)
	v_lshrrev_b32_e32 v49, 3, v47
	v_lshl_add_u32 v49, v49, 6, v46
	v_lshlrev_b32_e32 v49, 2, v49
	v_add_u32_e32 v49, 0x15000, v49
	ds_read_b32 v55, v49
	s_cmp_eq_u32 s68, 0
	s_cbranch_scc0 .Lsc_nomask_7
	v_cmp_gt_u32_e32 vcc, 3, v46
	s_nop 1
	v_cndmask_b32_e64 v120, v120, 0, vcc
	v_cndmask_b32_e64 v121, v121, 0, vcc
	v_cndmask_b32_e64 v122, v122, 0, vcc
	v_cndmask_b32_e64 v123, v123, 0, vcc
	v_cmp_gt_u32_e32 vcc, 2, v46
	s_nop 1
	v_cndmask_b32_e64 v124, v124, 0, vcc
	v_cndmask_b32_e64 v125, v125, 0, vcc
	v_cndmask_b32_e64 v126, v126, 0, vcc
	v_cndmask_b32_e64 v127, v127, 0, vcc
	v_cmp_gt_u32_e32 vcc, 1, v46
	s_nop 1
	v_cndmask_b32_e64 v128, v128, 0, vcc
	v_cndmask_b32_e64 v129, v129, 0, vcc
	v_cndmask_b32_e64 v130, v130, 0, vcc
	v_cndmask_b32_e64 v131, v131, 0, vcc
.Lsc_nomask_7:
	v_lshlrev_b32_e32 v49, 16, v120
	v_and_b32_e32 v120, 0xffff0000, v120
	v_fmac_f32_e32 v112, v136, v49
	v_fmac_f32_e32 v113, v137, v120
	v_lshlrev_b32_e32 v49, 16, v121
	v_and_b32_e32 v121, 0xffff0000, v121
	v_fmac_f32_e32 v114, v138, v49
	v_fmac_f32_e32 v115, v139, v121
	v_lshlrev_b32_e32 v49, 16, v122
	v_and_b32_e32 v122, 0xffff0000, v122
	v_fmac_f32_e32 v116, v140, v49
	v_fmac_f32_e32 v117, v141, v122
	v_lshlrev_b32_e32 v49, 16, v123
	v_and_b32_e32 v123, 0xffff0000, v123
	v_fmac_f32_e32 v118, v142, v49
	v_fmac_f32_e32 v119, v143, v123
	v_lshlrev_b32_e32 v49, 16, v124
	v_and_b32_e32 v124, 0xffff0000, v124
	v_fmac_f32_e32 v112, v144, v49
	v_fmac_f32_e32 v113, v145, v124
	v_lshlrev_b32_e32 v49, 16, v125
	v_and_b32_e32 v125, 0xffff0000, v125
	v_fmac_f32_e32 v114, v146, v49
	v_fmac_f32_e32 v115, v147, v125
	v_lshlrev_b32_e32 v49, 16, v126
	v_and_b32_e32 v126, 0xffff0000, v126
	v_fmac_f32_e32 v116, v148, v49
	v_fmac_f32_e32 v117, v149, v126
	v_lshlrev_b32_e32 v49, 16, v127
	v_and_b32_e32 v127, 0xffff0000, v127
	v_fmac_f32_e32 v118, v150, v49
	v_fmac_f32_e32 v119, v151, v127
	v_lshlrev_b32_e32 v49, 16, v128
	v_and_b32_e32 v128, 0xffff0000, v128
	v_fmac_f32_e32 v112, v152, v49
	v_fmac_f32_e32 v113, v153, v128
	v_lshlrev_b32_e32 v49, 16, v129
	v_and_b32_e32 v129, 0xffff0000, v129
	v_fmac_f32_e32 v114, v154, v49
	v_fmac_f32_e32 v115, v155, v129
	v_lshlrev_b32_e32 v49, 16, v130
	v_and_b32_e32 v130, 0xffff0000, v130
	v_fmac_f32_e32 v116, v156, v49
	v_fmac_f32_e32 v117, v157, v130
	v_lshlrev_b32_e32 v49, 16, v131
	v_and_b32_e32 v131, 0xffff0000, v131
	v_fmac_f32_e32 v118, v158, v49
	v_fmac_f32_e32 v119, v159, v131
	v_lshlrev_b32_e32 v49, 16, v132
	v_and_b32_e32 v132, 0xffff0000, v132
	v_fmac_f32_e32 v112, v160, v49
	v_fmac_f32_e32 v113, v161, v132
	v_lshlrev_b32_e32 v49, 16, v133
	v_and_b32_e32 v133, 0xffff0000, v133
	v_fmac_f32_e32 v114, v162, v49
	v_fmac_f32_e32 v115, v163, v133
	v_lshlrev_b32_e32 v49, 16, v134
	v_and_b32_e32 v134, 0xffff0000, v134
	v_fmac_f32_e32 v116, v252, v49
	v_fmac_f32_e32 v117, v253, v134
	v_lshlrev_b32_e32 v49, 16, v135
	v_and_b32_e32 v135, 0xffff0000, v135
	v_fmac_f32_e32 v118, v254, v49
	v_fmac_f32_e32 v119, v255, v135
	v_mul_f32_e32 v49, 0xbfb8aa3b, v112
	v_mul_f32_e32 v50, 0xbfb8aa3b, v113
	v_exp_f32_e32 v49, v49
	v_exp_f32_e32 v50, v50
	v_add_f32_e32 v49, 1.0, v49
	v_add_f32_e32 v50, 1.0, v50
	v_rcp_f32_e32 v49, v49
	v_rcp_f32_e32 v50, v50
	v_mul_f32_e32 v112, v112, v49
	v_mul_f32_e32 v113, v113, v50
	v_mul_f32_e32 v49, 0xbfb8aa3b, v114
	v_mul_f32_e32 v50, 0xbfb8aa3b, v115
	v_exp_f32_e32 v49, v49
	v_exp_f32_e32 v50, v50
	v_add_f32_e32 v49, 1.0, v49
	v_add_f32_e32 v50, 1.0, v50
	v_rcp_f32_e32 v49, v49
	v_rcp_f32_e32 v50, v50
	v_mul_f32_e32 v114, v114, v49
	v_mul_f32_e32 v115, v115, v50
	v_mul_f32_e32 v49, 0xbfb8aa3b, v116
	v_mul_f32_e32 v50, 0xbfb8aa3b, v117
	v_exp_f32_e32 v49, v49
	v_exp_f32_e32 v50, v50
	v_add_f32_e32 v49, 1.0, v49
	v_add_f32_e32 v50, 1.0, v50
	v_rcp_f32_e32 v49, v49
	v_rcp_f32_e32 v50, v50
	v_mul_f32_e32 v116, v116, v49
	v_mul_f32_e32 v117, v117, v50
	v_mul_f32_e32 v49, 0xbfb8aa3b, v118
	v_mul_f32_e32 v50, 0xbfb8aa3b, v119
	v_exp_f32_e32 v49, v49
	v_exp_f32_e32 v50, v50
	v_add_f32_e32 v49, 1.0, v49
	v_add_f32_e32 v50, 1.0, v50
	v_rcp_f32_e32 v49, v49
	v_rcp_f32_e32 v50, v50
	v_mul_f32_e32 v118, v118, v49
	v_mul_f32_e32 v119, v119, v50
	v_cvt_pk_bf16_f32 v120, v112, v113
	v_cvt_pk_bf16_f32 v121, v114, v115
	v_cvt_pk_bf16_f32 v122, v116, v117
	v_cvt_pk_bf16_f32 v123, v118, v119
	v_mul_u32_u24_e32 v49, 0xc00, v46
	v_lshl_add_u32 v49, v48, 1, v49
	global_store_dwordx4 v49, v[120:123], s[8:9]
	s_waitcnt lgkmcnt(0)
	v_mul_f32_e32 v244, v112, v55
	v_mul_f32_e32 v245, v113, v55
	v_mul_f32_e32 v246, v114, v55
	v_mul_f32_e32 v247, v115, v55
	v_mul_f32_e32 v248, v116, v55
	v_mul_f32_e32 v249, v117, v55
	v_mul_f32_e32 v250, v118, v55
	v_mul_f32_e32 v251, v119, v55
	v_cvt_pk_bf16_f32 v124, v244, v245
	v_cvt_pk_bf16_f32 v125, v246, v247
	v_cvt_pk_bf16_f32 v126, v248, v249
	v_cvt_pk_bf16_f32 v127, v250, v251
	v_mul_u32_u24_e32 v49, 0x420, v46
	v_lshl_add_u32 v49, v47, 4, v49
	v_mul_u32_u24_e32 v50, 0x120, v46
	v_lshl_add_u32 v50, v47, 4, v50
	v_add_u32_e32 v50, 0x10400, v50
	v_cmp_gt_u32_e32 vcc, 64, v47
	s_nop 1
	v_cndmask_b32_e32 v49, v50, v49, vcc
	v_cndmask_b32_e32 v124, v120, v124, vcc
	v_cndmask_b32_e32 v125, v121, v125, vcc
	v_cndmask_b32_e32 v126, v122, v126, vcc
	v_cndmask_b32_e32 v127, v123, v127, vcc
	v_cmp_gt_u32_e32 vcc, 80, v47
	s_and_saveexec_b64 s[12:13], vcc
	ds_write_b128 v49, v[124:127]
	s_or_b64 exec, exec, s[12:13]
	v_add_u32_e32 v49, 4608, v166
	v_mul_hi_i32 v46, v49, s67
	v_ashrrev_i32_e32 v46, 4, v46
	v_mul_lo_u32 v50, v46, s52
	v_sub_u32_e32 v47, v49, v50
	v_lshl_add_u32 v48, v47, 3, s71
	v_cmp_lt_u32_e32 vcc, 63, v47
	s_nop 1
	v_cndmask_b32_e64 v50, 0, 1, vcc
	v_mad_u32_u24 v48, v50, v42, v48
	v_cmp_lt_u32_e32 vcc, 79, v47
	s_nop 1
	v_cndmask_b32_e64 v50, 0, 1, vcc
	v_lshl_add_u32 v48, v50, 7, v48
	v_lshlrev_b32_e32 v50, 2, v48
	global_load_dwordx4 v[112:115], v50, s[78:79]
	global_load_dwordx4 v[116:119], v50, s[78:79] offset:16
	v_mul_u32_u24_e32 v51, 0x3600, v46
	v_lshl_add_u32 v51, v48, 1, v51
	s_add_u32 s4, s6, 0xffff8600
	s_addc_u32 s5, s7, -1
	global_load_dwordx4 v[120:123], v51, s[4:5]
	s_add_u32 s4, s6, 0xffffbc00
	s_addc_u32 s5, s7, -1
	global_load_dwordx4 v[124:127], v51, s[4:5]
	s_add_u32 s4, s6, 0xfffff200
	s_addc_u32 s5, s7, -1
	global_load_dwordx4 v[128:131], v51, s[4:5]
	s_add_u32 s4, s6, 0x2800
	s_addc_u32 s5, s7, 0
	global_load_dwordx4 v[132:135], v51, s[4:5]
	global_load_dwordx4 v[136:139], v50, s[92:93]
	global_load_dwordx4 v[140:143], v50, s[92:93] offset:16
	s_add_u32 s4, s92, 0x1800
	s_addc_u32 s5, s93, 0
	global_load_dwordx4 v[144:147], v50, s[4:5]
	global_load_dwordx4 v[148:151], v50, s[4:5] offset:16
	s_add_u32 s4, s92, 0x3000
	s_addc_u32 s5, s93, 0
	global_load_dwordx4 v[152:155], v50, s[4:5]
	global_load_dwordx4 v[156:159], v50, s[4:5] offset:16
	s_add_u32 s4, s92, 0x4800
	s_addc_u32 s5, s93, 0
	global_load_dwordx4 v[160:163], v50, s[4:5]
	global_load_dwordx4 v[252:255], v50, s[4:5] offset:16
	s_waitcnt vmcnt(15)
	v_lshrrev_b32_e32 v49, 3, v44
	v_lshl_add_u32 v49, v49, 6, v43
	v_lshlrev_b32_e32 v49, 2, v49
	v_add_u32_e32 v49, 0x15000, v49
	ds_read_b32 v55, v49
	s_cmp_eq_u32 s68, 0
	s_cbranch_scc0 .Lsc_nomask_8
	v_cmp_gt_u32_e32 vcc, 3, v43
	s_nop 1
	v_cndmask_b32_e64 v64, v64, 0, vcc
	v_cndmask_b32_e64 v65, v65, 0, vcc
	v_cndmask_b32_e64 v66, v66, 0, vcc
	v_cndmask_b32_e64 v67, v67, 0, vcc
	v_cmp_gt_u32_e32 vcc, 2, v43
	s_nop 1
	v_cndmask_b32_e64 v68, v68, 0, vcc
	v_cndmask_b32_e64 v69, v69, 0, vcc
	v_cndmask_b32_e64 v70, v70, 0, vcc
	v_cndmask_b32_e64 v71, v71, 0, vcc
	v_cmp_gt_u32_e32 vcc, 1, v43
	s_nop 1
	v_cndmask_b32_e64 v72, v72, 0, vcc
	v_cndmask_b32_e64 v73, v73, 0, vcc
	v_cndmask_b32_e64 v74, v74, 0, vcc
	v_cndmask_b32_e64 v75, v75, 0, vcc
.Lsc_nomask_8:
	v_lshlrev_b32_e32 v49, 16, v64
	v_and_b32_e32 v64, 0xffff0000, v64
	v_fmac_f32_e32 v56, v80, v49
	v_fmac_f32_e32 v57, v81, v64
	v_lshlrev_b32_e32 v49, 16, v65
	v_and_b32_e32 v65, 0xffff0000, v65
	v_fmac_f32_e32 v58, v82, v49
	v_fmac_f32_e32 v59, v83, v65
	v_lshlrev_b32_e32 v49, 16, v66
	v_and_b32_e32 v66, 0xffff0000, v66
	v_fmac_f32_e32 v60, v84, v49
	v_fmac_f32_e32 v61, v85, v66
	v_lshlrev_b32_e32 v49, 16, v67
	v_and_b32_e32 v67, 0xffff0000, v67
	v_fmac_f32_e32 v62, v86, v49
	v_fmac_f32_e32 v63, v87, v67
	v_lshlrev_b32_e32 v49, 16, v68
	v_and_b32_e32 v68, 0xffff0000, v68
	v_fmac_f32_e32 v56, v88, v49
	v_fmac_f32_e32 v57, v89, v68
	v_lshlrev_b32_e32 v49, 16, v69
	v_and_b32_e32 v69, 0xffff0000, v69
	v_fmac_f32_e32 v58, v90, v49
	v_fmac_f32_e32 v59, v91, v69
	v_lshlrev_b32_e32 v49, 16, v70
	v_and_b32_e32 v70, 0xffff0000, v70
	v_fmac_f32_e32 v60, v92, v49
	v_fmac_f32_e32 v61, v93, v70
	v_lshlrev_b32_e32 v49, 16, v71
	v_and_b32_e32 v71, 0xffff0000, v71
	v_fmac_f32_e32 v62, v94, v49
	v_fmac_f32_e32 v63, v95, v71
	v_lshlrev_b32_e32 v49, 16, v72
	v_and_b32_e32 v72, 0xffff0000, v72
	v_fmac_f32_e32 v56, v96, v49
	v_fmac_f32_e32 v57, v97, v72
	v_lshlrev_b32_e32 v49, 16, v73
	v_and_b32_e32 v73, 0xffff0000, v73
	v_fmac_f32_e32 v58, v98, v49
	v_fmac_f32_e32 v59, v99, v73
	v_lshlrev_b32_e32 v49, 16, v74
	v_and_b32_e32 v74, 0xffff0000, v74
	v_fmac_f32_e32 v60, v100, v49
	v_fmac_f32_e32 v61, v101, v74
	v_lshlrev_b32_e32 v49, 16, v75
	v_and_b32_e32 v75, 0xffff0000, v75
	v_fmac_f32_e32 v62, v102, v49
	v_fmac_f32_e32 v63, v103, v75
	v_lshlrev_b32_e32 v49, 16, v76
	v_and_b32_e32 v76, 0xffff0000, v76
	v_fmac_f32_e32 v56, v104, v49
	v_fmac_f32_e32 v57, v105, v76
	v_lshlrev_b32_e32 v49, 16, v77
	v_and_b32_e32 v77, 0xffff0000, v77
	v_fmac_f32_e32 v58, v106, v49
	v_fmac_f32_e32 v59, v107, v77
	v_lshlrev_b32_e32 v49, 16, v78
	v_and_b32_e32 v78, 0xffff0000, v78
	v_fmac_f32_e32 v60, v108, v49
	v_fmac_f32_e32 v61, v109, v78
	v_lshlrev_b32_e32 v49, 16, v79
	v_and_b32_e32 v79, 0xffff0000, v79
	v_fmac_f32_e32 v62, v110, v49
	v_fmac_f32_e32 v63, v111, v79
	v_mul_f32_e32 v49, 0xbfb8aa3b, v56
	v_mul_f32_e32 v50, 0xbfb8aa3b, v57
	v_exp_f32_e32 v49, v49
	v_exp_f32_e32 v50, v50
	v_add_f32_e32 v49, 1.0, v49
	v_add_f32_e32 v50, 1.0, v50
	v_rcp_f32_e32 v49, v49
	v_rcp_f32_e32 v50, v50
	v_mul_f32_e32 v56, v56, v49
	v_mul_f32_e32 v57, v57, v50
	v_mul_f32_e32 v49, 0xbfb8aa3b, v58
	v_mul_f32_e32 v50, 0xbfb8aa3b, v59
	v_exp_f32_e32 v49, v49
	v_exp_f32_e32 v50, v50
	v_add_f32_e32 v49, 1.0, v49
	v_add_f32_e32 v50, 1.0, v50
	v_rcp_f32_e32 v49, v49
	v_rcp_f32_e32 v50, v50
	v_mul_f32_e32 v58, v58, v49
	v_mul_f32_e32 v59, v59, v50
	v_mul_f32_e32 v49, 0xbfb8aa3b, v60
	v_mul_f32_e32 v50, 0xbfb8aa3b, v61
	v_exp_f32_e32 v49, v49
	v_exp_f32_e32 v50, v50
	v_add_f32_e32 v49, 1.0, v49
	v_add_f32_e32 v50, 1.0, v50
	v_rcp_f32_e32 v49, v49
	v_rcp_f32_e32 v50, v50
	v_mul_f32_e32 v60, v60, v49
	v_mul_f32_e32 v61, v61, v50
	v_mul_f32_e32 v49, 0xbfb8aa3b, v62
	v_mul_f32_e32 v50, 0xbfb8aa3b, v63
	v_exp_f32_e32 v49, v49
	v_exp_f32_e32 v50, v50
	v_add_f32_e32 v49, 1.0, v49
	v_add_f32_e32 v50, 1.0, v50
	v_rcp_f32_e32 v49, v49
	v_rcp_f32_e32 v50, v50
	v_mul_f32_e32 v62, v62, v49
	v_mul_f32_e32 v63, v63, v50
	v_cvt_pk_bf16_f32 v64, v56, v57
	v_cvt_pk_bf16_f32 v65, v58, v59
	v_cvt_pk_bf16_f32 v66, v60, v61
	v_cvt_pk_bf16_f32 v67, v62, v63
	v_mul_u32_u24_e32 v49, 0xc00, v43
	v_lshl_add_u32 v49, v45, 1, v49
	global_store_dwordx4 v49, v[64:67], s[8:9]
	s_waitcnt lgkmcnt(0)
	v_mul_f32_e32 v244, v56, v55
	v_mul_f32_e32 v245, v57, v55
	v_mul_f32_e32 v246, v58, v55
	v_mul_f32_e32 v247, v59, v55
	v_mul_f32_e32 v248, v60, v55
	v_mul_f32_e32 v249, v61, v55
	v_mul_f32_e32 v250, v62, v55
	v_mul_f32_e32 v251, v63, v55
	v_cvt_pk_bf16_f32 v68, v244, v245
	v_cvt_pk_bf16_f32 v69, v246, v247
	v_cvt_pk_bf16_f32 v70, v248, v249
	v_cvt_pk_bf16_f32 v71, v250, v251
	v_mul_u32_u24_e32 v49, 0x420, v43
	v_lshl_add_u32 v49, v44, 4, v49
	v_mul_u32_u24_e32 v50, 0x120, v43
	v_lshl_add_u32 v50, v44, 4, v50
	v_add_u32_e32 v50, 0x10400, v50
	v_cmp_gt_u32_e32 vcc, 64, v44
	s_nop 1
	v_cndmask_b32_e32 v49, v50, v49, vcc
	v_cndmask_b32_e32 v68, v64, v68, vcc
	v_cndmask_b32_e32 v69, v65, v69, vcc
	v_cndmask_b32_e32 v70, v66, v70, vcc
	v_cndmask_b32_e32 v71, v67, v71, vcc
	v_cmp_gt_u32_e32 vcc, 80, v44
	s_and_saveexec_b64 s[12:13], vcc
	ds_write_b128 v49, v[68:71]
	s_or_b64 exec, exec, s[12:13]
	v_add_u32_e32 v49, 5120, v166
	v_mul_hi_i32 v43, v49, s67
	v_ashrrev_i32_e32 v43, 4, v43
	v_mul_lo_u32 v50, v43, s52
	v_sub_u32_e32 v44, v49, v50
	v_lshl_add_u32 v45, v44, 3, s71
	v_cmp_lt_u32_e32 vcc, 63, v44
	s_nop 1
	v_cndmask_b32_e64 v50, 0, 1, vcc
	v_mad_u32_u24 v45, v50, v42, v45
	v_cmp_lt_u32_e32 vcc, 79, v44
	s_nop 1
	v_cndmask_b32_e64 v50, 0, 1, vcc
	v_lshl_add_u32 v45, v50, 7, v45
	v_lshlrev_b32_e32 v50, 2, v45
	global_load_dwordx4 v[56:59], v50, s[78:79]
	global_load_dwordx4 v[60:63], v50, s[78:79] offset:16
	v_mul_u32_u24_e32 v51, 0x3600, v43
	v_lshl_add_u32 v51, v45, 1, v51
	s_add_u32 s4, s6, 0xffff8600
	s_addc_u32 s5, s7, -1
	global_load_dwordx4 v[64:67], v51, s[4:5]
	s_add_u32 s4, s6, 0xffffbc00
	s_addc_u32 s5, s7, -1
	global_load_dwordx4 v[68:71], v51, s[4:5]
	s_add_u32 s4, s6, 0xfffff200
	s_addc_u32 s5, s7, -1
	global_load_dwordx4 v[72:75], v51, s[4:5]
	s_add_u32 s4, s6, 0x2800
	s_addc_u32 s5, s7, 0
	global_load_dwordx4 v[76:79], v51, s[4:5]
	global_load_dwordx4 v[80:83], v50, s[92:93]
	global_load_dwordx4 v[84:87], v50, s[92:93] offset:16
	s_add_u32 s4, s92, 0x1800
	s_addc_u32 s5, s93, 0
	global_load_dwordx4 v[88:91], v50, s[4:5]
	global_load_dwordx4 v[92:95], v50, s[4:5] offset:16
	s_add_u32 s4, s92, 0x3000
	s_addc_u32 s5, s93, 0
	global_load_dwordx4 v[96:99], v50, s[4:5]
	global_load_dwordx4 v[100:103], v50, s[4:5] offset:16
	s_add_u32 s4, s92, 0x4800
	s_addc_u32 s5, s93, 0
	global_load_dwordx4 v[104:107], v50, s[4:5]
	global_load_dwordx4 v[108:111], v50, s[4:5] offset:16
	s_waitcnt vmcnt(15)
	v_lshrrev_b32_e32 v49, 3, v47
	v_lshl_add_u32 v49, v49, 6, v46
	v_lshlrev_b32_e32 v49, 2, v49
	v_add_u32_e32 v49, 0x15000, v49
	ds_read_b32 v55, v49
	s_cmp_eq_u32 s68, 0
	s_cbranch_scc0 .Lsc_nomask_9
	v_cmp_gt_u32_e32 vcc, 3, v46
	s_nop 1
	v_cndmask_b32_e64 v120, v120, 0, vcc
	v_cndmask_b32_e64 v121, v121, 0, vcc
	v_cndmask_b32_e64 v122, v122, 0, vcc
	v_cndmask_b32_e64 v123, v123, 0, vcc
	v_cmp_gt_u32_e32 vcc, 2, v46
	s_nop 1
	v_cndmask_b32_e64 v124, v124, 0, vcc
	v_cndmask_b32_e64 v125, v125, 0, vcc
	v_cndmask_b32_e64 v126, v126, 0, vcc
	v_cndmask_b32_e64 v127, v127, 0, vcc
	v_cmp_gt_u32_e32 vcc, 1, v46
	s_nop 1
	v_cndmask_b32_e64 v128, v128, 0, vcc
	v_cndmask_b32_e64 v129, v129, 0, vcc
	v_cndmask_b32_e64 v130, v130, 0, vcc
	v_cndmask_b32_e64 v131, v131, 0, vcc
.Lsc_nomask_9:
	v_lshlrev_b32_e32 v49, 16, v120
	v_and_b32_e32 v120, 0xffff0000, v120
	v_fmac_f32_e32 v112, v136, v49
	v_fmac_f32_e32 v113, v137, v120
	v_lshlrev_b32_e32 v49, 16, v121
	v_and_b32_e32 v121, 0xffff0000, v121
	v_fmac_f32_e32 v114, v138, v49
	v_fmac_f32_e32 v115, v139, v121
	v_lshlrev_b32_e32 v49, 16, v122
	v_and_b32_e32 v122, 0xffff0000, v122
	v_fmac_f32_e32 v116, v140, v49
	v_fmac_f32_e32 v117, v141, v122
	v_lshlrev_b32_e32 v49, 16, v123
	v_and_b32_e32 v123, 0xffff0000, v123
	v_fmac_f32_e32 v118, v142, v49
	v_fmac_f32_e32 v119, v143, v123
	v_lshlrev_b32_e32 v49, 16, v124
	v_and_b32_e32 v124, 0xffff0000, v124
	v_fmac_f32_e32 v112, v144, v49
	v_fmac_f32_e32 v113, v145, v124
	v_lshlrev_b32_e32 v49, 16, v125
	v_and_b32_e32 v125, 0xffff0000, v125
	v_fmac_f32_e32 v114, v146, v49
	v_fmac_f32_e32 v115, v147, v125
	v_lshlrev_b32_e32 v49, 16, v126
	v_and_b32_e32 v126, 0xffff0000, v126
	v_fmac_f32_e32 v116, v148, v49
	v_fmac_f32_e32 v117, v149, v126
	v_lshlrev_b32_e32 v49, 16, v127
	v_and_b32_e32 v127, 0xffff0000, v127
	v_fmac_f32_e32 v118, v150, v49
	v_fmac_f32_e32 v119, v151, v127
	v_lshlrev_b32_e32 v49, 16, v128
	v_and_b32_e32 v128, 0xffff0000, v128
	v_fmac_f32_e32 v112, v152, v49
	v_fmac_f32_e32 v113, v153, v128
	v_lshlrev_b32_e32 v49, 16, v129
	v_and_b32_e32 v129, 0xffff0000, v129
	v_fmac_f32_e32 v114, v154, v49
	v_fmac_f32_e32 v115, v155, v129
	v_lshlrev_b32_e32 v49, 16, v130
	v_and_b32_e32 v130, 0xffff0000, v130
	v_fmac_f32_e32 v116, v156, v49
	v_fmac_f32_e32 v117, v157, v130
	v_lshlrev_b32_e32 v49, 16, v131
	v_and_b32_e32 v131, 0xffff0000, v131
	v_fmac_f32_e32 v118, v158, v49
	v_fmac_f32_e32 v119, v159, v131
	v_lshlrev_b32_e32 v49, 16, v132
	v_and_b32_e32 v132, 0xffff0000, v132
	v_fmac_f32_e32 v112, v160, v49
	v_fmac_f32_e32 v113, v161, v132
	v_lshlrev_b32_e32 v49, 16, v133
	v_and_b32_e32 v133, 0xffff0000, v133
	v_fmac_f32_e32 v114, v162, v49
	v_fmac_f32_e32 v115, v163, v133
	v_lshlrev_b32_e32 v49, 16, v134
	v_and_b32_e32 v134, 0xffff0000, v134
	v_fmac_f32_e32 v116, v252, v49
	v_fmac_f32_e32 v117, v253, v134
	v_lshlrev_b32_e32 v49, 16, v135
	v_and_b32_e32 v135, 0xffff0000, v135
	v_fmac_f32_e32 v118, v254, v49
	v_fmac_f32_e32 v119, v255, v135
	v_mul_f32_e32 v49, 0xbfb8aa3b, v112
	v_mul_f32_e32 v50, 0xbfb8aa3b, v113
	v_exp_f32_e32 v49, v49
	v_exp_f32_e32 v50, v50
	v_add_f32_e32 v49, 1.0, v49
	v_add_f32_e32 v50, 1.0, v50
	v_rcp_f32_e32 v49, v49
	v_rcp_f32_e32 v50, v50
	v_mul_f32_e32 v112, v112, v49
	v_mul_f32_e32 v113, v113, v50
	v_mul_f32_e32 v49, 0xbfb8aa3b, v114
	v_mul_f32_e32 v50, 0xbfb8aa3b, v115
	v_exp_f32_e32 v49, v49
	v_exp_f32_e32 v50, v50
	v_add_f32_e32 v49, 1.0, v49
	v_add_f32_e32 v50, 1.0, v50
	v_rcp_f32_e32 v49, v49
	v_rcp_f32_e32 v50, v50
	v_mul_f32_e32 v114, v114, v49
	v_mul_f32_e32 v115, v115, v50
	v_mul_f32_e32 v49, 0xbfb8aa3b, v116
	v_mul_f32_e32 v50, 0xbfb8aa3b, v117
	v_exp_f32_e32 v49, v49
	v_exp_f32_e32 v50, v50
	v_add_f32_e32 v49, 1.0, v49
	v_add_f32_e32 v50, 1.0, v50
	v_rcp_f32_e32 v49, v49
	v_rcp_f32_e32 v50, v50
	v_mul_f32_e32 v116, v116, v49
	v_mul_f32_e32 v117, v117, v50
	v_mul_f32_e32 v49, 0xbfb8aa3b, v118
	v_mul_f32_e32 v50, 0xbfb8aa3b, v119
	v_exp_f32_e32 v49, v49
	v_exp_f32_e32 v50, v50
	v_add_f32_e32 v49, 1.0, v49
	v_add_f32_e32 v50, 1.0, v50
	v_rcp_f32_e32 v49, v49
	v_rcp_f32_e32 v50, v50
	v_mul_f32_e32 v118, v118, v49
	v_mul_f32_e32 v119, v119, v50
	v_cvt_pk_bf16_f32 v120, v112, v113
	v_cvt_pk_bf16_f32 v121, v114, v115
	v_cvt_pk_bf16_f32 v122, v116, v117
	v_cvt_pk_bf16_f32 v123, v118, v119
	v_mul_u32_u24_e32 v49, 0xc00, v46
	v_lshl_add_u32 v49, v48, 1, v49
	global_store_dwordx4 v49, v[120:123], s[8:9]
	s_waitcnt lgkmcnt(0)
	v_mul_f32_e32 v244, v112, v55
	v_mul_f32_e32 v245, v113, v55
	v_mul_f32_e32 v246, v114, v55
	v_mul_f32_e32 v247, v115, v55
	v_mul_f32_e32 v248, v116, v55
	v_mul_f32_e32 v249, v117, v55
	v_mul_f32_e32 v250, v118, v55
	v_mul_f32_e32 v251, v119, v55
	v_cvt_pk_bf16_f32 v124, v244, v245
	v_cvt_pk_bf16_f32 v125, v246, v247
	v_cvt_pk_bf16_f32 v126, v248, v249
	v_cvt_pk_bf16_f32 v127, v250, v251
	v_mul_u32_u24_e32 v49, 0x420, v46
	v_lshl_add_u32 v49, v47, 4, v49
	v_mul_u32_u24_e32 v50, 0x120, v46
	v_lshl_add_u32 v50, v47, 4, v50
	v_add_u32_e32 v50, 0x10400, v50
	v_cmp_gt_u32_e32 vcc, 64, v47
	s_nop 1
	v_cndmask_b32_e32 v49, v50, v49, vcc
	v_cndmask_b32_e32 v124, v120, v124, vcc
	v_cndmask_b32_e32 v125, v121, v125, vcc
	v_cndmask_b32_e32 v126, v122, v126, vcc
	v_cndmask_b32_e32 v127, v123, v127, vcc
	v_cmp_gt_u32_e32 vcc, 80, v47
	s_and_saveexec_b64 s[12:13], vcc
	ds_write_b128 v49, v[124:127]
	s_or_b64 exec, exec, s[12:13]
	v_add_u32_e32 v49, 5632, v166
	v_mul_hi_i32 v46, v49, s67
	v_ashrrev_i32_e32 v46, 4, v46
	v_mul_lo_u32 v50, v46, s52
	v_sub_u32_e32 v47, v49, v50
	v_lshl_add_u32 v48, v47, 3, s71
	v_cmp_lt_u32_e32 vcc, 63, v47
	s_nop 1
	v_cndmask_b32_e64 v50, 0, 1, vcc
	v_mad_u32_u24 v48, v50, v42, v48
	v_cmp_lt_u32_e32 vcc, 79, v47
	s_nop 1
	v_cndmask_b32_e64 v50, 0, 1, vcc
	v_lshl_add_u32 v48, v50, 7, v48
	v_lshlrev_b32_e32 v50, 2, v48
	global_load_dwordx4 v[112:115], v50, s[78:79]
	global_load_dwordx4 v[116:119], v50, s[78:79] offset:16
	v_mul_u32_u24_e32 v51, 0x3600, v46
	v_lshl_add_u32 v51, v48, 1, v51
	s_add_u32 s4, s6, 0xffff8600
	s_addc_u32 s5, s7, -1
	global_load_dwordx4 v[120:123], v51, s[4:5]
	s_add_u32 s4, s6, 0xffffbc00
	s_addc_u32 s5, s7, -1
	global_load_dwordx4 v[124:127], v51, s[4:5]
	s_add_u32 s4, s6, 0xfffff200
	s_addc_u32 s5, s7, -1
	global_load_dwordx4 v[128:131], v51, s[4:5]
	s_add_u32 s4, s6, 0x2800
	s_addc_u32 s5, s7, 0
	global_load_dwordx4 v[132:135], v51, s[4:5]
	global_load_dwordx4 v[136:139], v50, s[92:93]
	global_load_dwordx4 v[140:143], v50, s[92:93] offset:16
	s_add_u32 s4, s92, 0x1800
	s_addc_u32 s5, s93, 0
	global_load_dwordx4 v[144:147], v50, s[4:5]
	global_load_dwordx4 v[148:151], v50, s[4:5] offset:16
	s_add_u32 s4, s92, 0x3000
	s_addc_u32 s5, s93, 0
	global_load_dwordx4 v[152:155], v50, s[4:5]
	global_load_dwordx4 v[156:159], v50, s[4:5] offset:16
	s_add_u32 s4, s92, 0x4800
	s_addc_u32 s5, s93, 0
	global_load_dwordx4 v[160:163], v50, s[4:5]
	global_load_dwordx4 v[252:255], v50, s[4:5] offset:16
	s_waitcnt vmcnt(15)
	v_lshrrev_b32_e32 v49, 3, v44
	v_lshl_add_u32 v49, v49, 6, v43
	v_lshlrev_b32_e32 v49, 2, v49
	v_add_u32_e32 v49, 0x15000, v49
	ds_read_b32 v55, v49
	s_cmp_eq_u32 s68, 0
	s_cbranch_scc0 .Lsc_nomask_10
	v_cmp_gt_u32_e32 vcc, 3, v43
	s_nop 1
	v_cndmask_b32_e64 v64, v64, 0, vcc
	v_cndmask_b32_e64 v65, v65, 0, vcc
	v_cndmask_b32_e64 v66, v66, 0, vcc
	v_cndmask_b32_e64 v67, v67, 0, vcc
	v_cmp_gt_u32_e32 vcc, 2, v43
	s_nop 1
	v_cndmask_b32_e64 v68, v68, 0, vcc
	v_cndmask_b32_e64 v69, v69, 0, vcc
	v_cndmask_b32_e64 v70, v70, 0, vcc
	v_cndmask_b32_e64 v71, v71, 0, vcc
	v_cmp_gt_u32_e32 vcc, 1, v43
	s_nop 1
	v_cndmask_b32_e64 v72, v72, 0, vcc
	v_cndmask_b32_e64 v73, v73, 0, vcc
	v_cndmask_b32_e64 v74, v74, 0, vcc
	v_cndmask_b32_e64 v75, v75, 0, vcc
.Lsc_nomask_10:
	v_lshlrev_b32_e32 v49, 16, v64
	v_and_b32_e32 v64, 0xffff0000, v64
	v_fmac_f32_e32 v56, v80, v49
	v_fmac_f32_e32 v57, v81, v64
	v_lshlrev_b32_e32 v49, 16, v65
	v_and_b32_e32 v65, 0xffff0000, v65
	v_fmac_f32_e32 v58, v82, v49
	v_fmac_f32_e32 v59, v83, v65
	v_lshlrev_b32_e32 v49, 16, v66
	v_and_b32_e32 v66, 0xffff0000, v66
	v_fmac_f32_e32 v60, v84, v49
	v_fmac_f32_e32 v61, v85, v66
	v_lshlrev_b32_e32 v49, 16, v67
	v_and_b32_e32 v67, 0xffff0000, v67
	v_fmac_f32_e32 v62, v86, v49
	v_fmac_f32_e32 v63, v87, v67
	v_lshlrev_b32_e32 v49, 16, v68
	v_and_b32_e32 v68, 0xffff0000, v68
	v_fmac_f32_e32 v56, v88, v49
	v_fmac_f32_e32 v57, v89, v68
	v_lshlrev_b32_e32 v49, 16, v69
	v_and_b32_e32 v69, 0xffff0000, v69
	v_fmac_f32_e32 v58, v90, v49
	v_fmac_f32_e32 v59, v91, v69
	v_lshlrev_b32_e32 v49, 16, v70
	v_and_b32_e32 v70, 0xffff0000, v70
	v_fmac_f32_e32 v60, v92, v49
	v_fmac_f32_e32 v61, v93, v70
	v_lshlrev_b32_e32 v49, 16, v71
	v_and_b32_e32 v71, 0xffff0000, v71
	v_fmac_f32_e32 v62, v94, v49
	v_fmac_f32_e32 v63, v95, v71
	v_lshlrev_b32_e32 v49, 16, v72
	v_and_b32_e32 v72, 0xffff0000, v72
	v_fmac_f32_e32 v56, v96, v49
	v_fmac_f32_e32 v57, v97, v72
	v_lshlrev_b32_e32 v49, 16, v73
	v_and_b32_e32 v73, 0xffff0000, v73
	v_fmac_f32_e32 v58, v98, v49
	v_fmac_f32_e32 v59, v99, v73
	v_lshlrev_b32_e32 v49, 16, v74
	v_and_b32_e32 v74, 0xffff0000, v74
	v_fmac_f32_e32 v60, v100, v49
	v_fmac_f32_e32 v61, v101, v74
	v_lshlrev_b32_e32 v49, 16, v75
	v_and_b32_e32 v75, 0xffff0000, v75
	v_fmac_f32_e32 v62, v102, v49
	v_fmac_f32_e32 v63, v103, v75
	v_lshlrev_b32_e32 v49, 16, v76
	v_and_b32_e32 v76, 0xffff0000, v76
	v_fmac_f32_e32 v56, v104, v49
	v_fmac_f32_e32 v57, v105, v76
	v_lshlrev_b32_e32 v49, 16, v77
	v_and_b32_e32 v77, 0xffff0000, v77
	v_fmac_f32_e32 v58, v106, v49
	v_fmac_f32_e32 v59, v107, v77
	v_lshlrev_b32_e32 v49, 16, v78
	v_and_b32_e32 v78, 0xffff0000, v78
	v_fmac_f32_e32 v60, v108, v49
	v_fmac_f32_e32 v61, v109, v78
	v_lshlrev_b32_e32 v49, 16, v79
	v_and_b32_e32 v79, 0xffff0000, v79
	v_fmac_f32_e32 v62, v110, v49
	v_fmac_f32_e32 v63, v111, v79
	v_mul_f32_e32 v49, 0xbfb8aa3b, v56
	v_mul_f32_e32 v50, 0xbfb8aa3b, v57
	v_exp_f32_e32 v49, v49
	v_exp_f32_e32 v50, v50
	v_add_f32_e32 v49, 1.0, v49
	v_add_f32_e32 v50, 1.0, v50
	v_rcp_f32_e32 v49, v49
	v_rcp_f32_e32 v50, v50
	v_mul_f32_e32 v56, v56, v49
	v_mul_f32_e32 v57, v57, v50
	v_mul_f32_e32 v49, 0xbfb8aa3b, v58
	v_mul_f32_e32 v50, 0xbfb8aa3b, v59
	v_exp_f32_e32 v49, v49
	v_exp_f32_e32 v50, v50
	v_add_f32_e32 v49, 1.0, v49
	v_add_f32_e32 v50, 1.0, v50
	v_rcp_f32_e32 v49, v49
	v_rcp_f32_e32 v50, v50
	v_mul_f32_e32 v58, v58, v49
	v_mul_f32_e32 v59, v59, v50
	v_mul_f32_e32 v49, 0xbfb8aa3b, v60
	v_mul_f32_e32 v50, 0xbfb8aa3b, v61
	v_exp_f32_e32 v49, v49
	v_exp_f32_e32 v50, v50
	v_add_f32_e32 v49, 1.0, v49
	v_add_f32_e32 v50, 1.0, v50
	v_rcp_f32_e32 v49, v49
	v_rcp_f32_e32 v50, v50
	v_mul_f32_e32 v60, v60, v49
	v_mul_f32_e32 v61, v61, v50
	v_mul_f32_e32 v49, 0xbfb8aa3b, v62
	v_mul_f32_e32 v50, 0xbfb8aa3b, v63
	v_exp_f32_e32 v49, v49
	v_exp_f32_e32 v50, v50
	v_add_f32_e32 v49, 1.0, v49
	v_add_f32_e32 v50, 1.0, v50
	v_rcp_f32_e32 v49, v49
	v_rcp_f32_e32 v50, v50
	v_mul_f32_e32 v62, v62, v49
	v_mul_f32_e32 v63, v63, v50
	v_cvt_pk_bf16_f32 v64, v56, v57
	v_cvt_pk_bf16_f32 v65, v58, v59
	v_cvt_pk_bf16_f32 v66, v60, v61
	v_cvt_pk_bf16_f32 v67, v62, v63
	v_mul_u32_u24_e32 v49, 0xc00, v43
	v_lshl_add_u32 v49, v45, 1, v49
	global_store_dwordx4 v49, v[64:67], s[8:9]
	s_waitcnt lgkmcnt(0)
	v_mul_f32_e32 v244, v56, v55
	v_mul_f32_e32 v245, v57, v55
	v_mul_f32_e32 v246, v58, v55
	v_mul_f32_e32 v247, v59, v55
	v_mul_f32_e32 v248, v60, v55
	v_mul_f32_e32 v249, v61, v55
	v_mul_f32_e32 v250, v62, v55
	v_mul_f32_e32 v251, v63, v55
	v_cvt_pk_bf16_f32 v68, v244, v245
	v_cvt_pk_bf16_f32 v69, v246, v247
	v_cvt_pk_bf16_f32 v70, v248, v249
	v_cvt_pk_bf16_f32 v71, v250, v251
	v_mul_u32_u24_e32 v49, 0x420, v43
	v_lshl_add_u32 v49, v44, 4, v49
	v_mul_u32_u24_e32 v50, 0x120, v43
	v_lshl_add_u32 v50, v44, 4, v50
	v_add_u32_e32 v50, 0x10400, v50
	v_cmp_gt_u32_e32 vcc, 64, v44
	s_nop 1
	v_cndmask_b32_e32 v49, v50, v49, vcc
	v_cndmask_b32_e32 v68, v64, v68, vcc
	v_cndmask_b32_e32 v69, v65, v69, vcc
	v_cndmask_b32_e32 v70, v66, v70, vcc
	v_cndmask_b32_e32 v71, v67, v71, vcc
	v_cmp_gt_u32_e32 vcc, 80, v44
	s_and_saveexec_b64 s[12:13], vcc
	ds_write_b128 v49, v[68:71]
	s_or_b64 exec, exec, s[12:13]
	s_waitcnt vmcnt(1)
	v_lshrrev_b32_e32 v49, 3, v47
	v_lshl_add_u32 v49, v49, 6, v46
	v_lshlrev_b32_e32 v49, 2, v49
	v_add_u32_e32 v49, 0x15000, v49
	ds_read_b32 v55, v49
	s_cmp_eq_u32 s68, 0
	s_cbranch_scc0 .Lsc_nomask_11
	v_cmp_gt_u32_e32 vcc, 3, v46
	s_nop 1
	v_cndmask_b32_e64 v120, v120, 0, vcc
	v_cndmask_b32_e64 v121, v121, 0, vcc
	v_cndmask_b32_e64 v122, v122, 0, vcc
	v_cndmask_b32_e64 v123, v123, 0, vcc
	v_cmp_gt_u32_e32 vcc, 2, v46
	s_nop 1
	v_cndmask_b32_e64 v124, v124, 0, vcc
	v_cndmask_b32_e64 v125, v125, 0, vcc
	v_cndmask_b32_e64 v126, v126, 0, vcc
	v_cndmask_b32_e64 v127, v127, 0, vcc
	v_cmp_gt_u32_e32 vcc, 1, v46
	s_nop 1
	v_cndmask_b32_e64 v128, v128, 0, vcc
	v_cndmask_b32_e64 v129, v129, 0, vcc
	v_cndmask_b32_e64 v130, v130, 0, vcc
	v_cndmask_b32_e64 v131, v131, 0, vcc
.Lsc_nomask_11:
	v_lshlrev_b32_e32 v49, 16, v120
	v_and_b32_e32 v120, 0xffff0000, v120
	v_fmac_f32_e32 v112, v136, v49
	v_fmac_f32_e32 v113, v137, v120
	v_lshlrev_b32_e32 v49, 16, v121
	v_and_b32_e32 v121, 0xffff0000, v121
	v_fmac_f32_e32 v114, v138, v49
	v_fmac_f32_e32 v115, v139, v121
	v_lshlrev_b32_e32 v49, 16, v122
	v_and_b32_e32 v122, 0xffff0000, v122
	v_fmac_f32_e32 v116, v140, v49
	v_fmac_f32_e32 v117, v141, v122
	v_lshlrev_b32_e32 v49, 16, v123
	v_and_b32_e32 v123, 0xffff0000, v123
	v_fmac_f32_e32 v118, v142, v49
	v_fmac_f32_e32 v119, v143, v123
	v_lshlrev_b32_e32 v49, 16, v124
	v_and_b32_e32 v124, 0xffff0000, v124
	v_fmac_f32_e32 v112, v144, v49
	v_fmac_f32_e32 v113, v145, v124
	v_lshlrev_b32_e32 v49, 16, v125
	v_and_b32_e32 v125, 0xffff0000, v125
	v_fmac_f32_e32 v114, v146, v49
	v_fmac_f32_e32 v115, v147, v125
	v_lshlrev_b32_e32 v49, 16, v126
	v_and_b32_e32 v126, 0xffff0000, v126
	v_fmac_f32_e32 v116, v148, v49
	v_fmac_f32_e32 v117, v149, v126
	v_lshlrev_b32_e32 v49, 16, v127
	v_and_b32_e32 v127, 0xffff0000, v127
	v_fmac_f32_e32 v118, v150, v49
	v_fmac_f32_e32 v119, v151, v127
	v_lshlrev_b32_e32 v49, 16, v128
	v_and_b32_e32 v128, 0xffff0000, v128
	v_fmac_f32_e32 v112, v152, v49
	v_fmac_f32_e32 v113, v153, v128
	v_lshlrev_b32_e32 v49, 16, v129
	v_and_b32_e32 v129, 0xffff0000, v129
	v_fmac_f32_e32 v114, v154, v49
	v_fmac_f32_e32 v115, v155, v129
	v_lshlrev_b32_e32 v49, 16, v130
	v_and_b32_e32 v130, 0xffff0000, v130
	v_fmac_f32_e32 v116, v156, v49
	v_fmac_f32_e32 v117, v157, v130
	v_lshlrev_b32_e32 v49, 16, v131
	v_and_b32_e32 v131, 0xffff0000, v131
	v_fmac_f32_e32 v118, v158, v49
	v_fmac_f32_e32 v119, v159, v131
	v_lshlrev_b32_e32 v49, 16, v132
	v_and_b32_e32 v132, 0xffff0000, v132
	v_fmac_f32_e32 v112, v160, v49
	v_fmac_f32_e32 v113, v161, v132
	v_lshlrev_b32_e32 v49, 16, v133
	v_and_b32_e32 v133, 0xffff0000, v133
	v_fmac_f32_e32 v114, v162, v49
	v_fmac_f32_e32 v115, v163, v133
	v_lshlrev_b32_e32 v49, 16, v134
	v_and_b32_e32 v134, 0xffff0000, v134
	v_fmac_f32_e32 v116, v252, v49
	v_fmac_f32_e32 v117, v253, v134
	v_lshlrev_b32_e32 v49, 16, v135
	v_and_b32_e32 v135, 0xffff0000, v135
	v_fmac_f32_e32 v118, v254, v49
	v_fmac_f32_e32 v119, v255, v135
	v_mul_f32_e32 v49, 0xbfb8aa3b, v112
	v_mul_f32_e32 v50, 0xbfb8aa3b, v113
	v_exp_f32_e32 v49, v49
	v_exp_f32_e32 v50, v50
	v_add_f32_e32 v49, 1.0, v49
	v_add_f32_e32 v50, 1.0, v50
	v_rcp_f32_e32 v49, v49
	v_rcp_f32_e32 v50, v50
	v_mul_f32_e32 v112, v112, v49
	v_mul_f32_e32 v113, v113, v50
	v_mul_f32_e32 v49, 0xbfb8aa3b, v114
	v_mul_f32_e32 v50, 0xbfb8aa3b, v115
	v_exp_f32_e32 v49, v49
	v_exp_f32_e32 v50, v50
	v_add_f32_e32 v49, 1.0, v49
	v_add_f32_e32 v50, 1.0, v50
	v_rcp_f32_e32 v49, v49
	v_rcp_f32_e32 v50, v50
	v_mul_f32_e32 v114, v114, v49
	v_mul_f32_e32 v115, v115, v50
	v_mul_f32_e32 v49, 0xbfb8aa3b, v116
	v_mul_f32_e32 v50, 0xbfb8aa3b, v117
	v_exp_f32_e32 v49, v49
	v_exp_f32_e32 v50, v50
	v_add_f32_e32 v49, 1.0, v49
	v_add_f32_e32 v50, 1.0, v50
	v_rcp_f32_e32 v49, v49
	v_rcp_f32_e32 v50, v50
	v_mul_f32_e32 v116, v116, v49
	v_mul_f32_e32 v117, v117, v50
	v_mul_f32_e32 v49, 0xbfb8aa3b, v118
	v_mul_f32_e32 v50, 0xbfb8aa3b, v119
	v_exp_f32_e32 v49, v49
	v_exp_f32_e32 v50, v50
	v_add_f32_e32 v49, 1.0, v49
	v_add_f32_e32 v50, 1.0, v50
	v_rcp_f32_e32 v49, v49
	v_rcp_f32_e32 v50, v50
	v_mul_f32_e32 v118, v118, v49
	v_mul_f32_e32 v119, v119, v50
	v_cvt_pk_bf16_f32 v120, v112, v113
	v_cvt_pk_bf16_f32 v121, v114, v115
	v_cvt_pk_bf16_f32 v122, v116, v117
	v_cvt_pk_bf16_f32 v123, v118, v119
	v_mul_u32_u24_e32 v49, 0xc00, v46
	v_lshl_add_u32 v49, v48, 1, v49
	global_store_dwordx4 v49, v[120:123], s[8:9]
	s_waitcnt lgkmcnt(0)
	v_mul_f32_e32 v244, v112, v55
	v_mul_f32_e32 v245, v113, v55
	v_mul_f32_e32 v246, v114, v55
	v_mul_f32_e32 v247, v115, v55
	v_mul_f32_e32 v248, v116, v55
	v_mul_f32_e32 v249, v117, v55
	v_mul_f32_e32 v250, v118, v55
	v_mul_f32_e32 v251, v119, v55
	v_cvt_pk_bf16_f32 v124, v244, v245
	v_cvt_pk_bf16_f32 v125, v246, v247
	v_cvt_pk_bf16_f32 v126, v248, v249
	v_cvt_pk_bf16_f32 v127, v250, v251
	v_mul_u32_u24_e32 v49, 0x420, v46
	v_lshl_add_u32 v49, v47, 4, v49
	v_mul_u32_u24_e32 v50, 0x120, v46
	v_lshl_add_u32 v50, v47, 4, v50
	v_add_u32_e32 v50, 0x10400, v50
	v_cmp_gt_u32_e32 vcc, 64, v47
	s_nop 1
	v_cndmask_b32_e32 v49, v50, v49, vcc
	v_cndmask_b32_e32 v124, v120, v124, vcc
	v_cndmask_b32_e32 v125, v121, v125, vcc
	v_cndmask_b32_e32 v126, v122, v126, vcc
	v_cndmask_b32_e32 v127, v123, v127, vcc
	v_cmp_gt_u32_e32 vcc, 80, v47
	s_and_saveexec_b64 s[12:13], vcc
	ds_write_b128 v49, v[124:127]
	s_or_b64 exec, exec, s[12:13]
	s_branch .LBB0_209
